# P3 C-projection: the four XT fragment LDS reads of each cluster issued together with counted waits (was read-wait-MFMA x3 in series)
# baseline (speedup 1.0000x reference)
.LBB0_405:
	s_or_b32 s10, s40, s18
	v_lshl_or_b32 v0, s10, 7, v129
	v_ashrrev_i32_e32 v1, 31, v0
	v_lshl_add_u64 v[0:1], v[0:1], 2, s[16:17]
	global_load_dwordx2 v[114:115], v[0:1], off
	global_load_dwordx2 v[112:113], v[0:1], off offset:256
	s_lshl_b32 s14, s10, 2
	s_lshl_b64 s[38:39], s[14:15], 10
	v_cndmask_b32_e64 v232, v194, v120, s[6:7]
	v_cndmask_b32_e64 v233, v195, v121, s[6:7]
	v_cndmask_b32_e64 v234, v198, v122, s[6:7]
	v_cndmask_b32_e64 v235, v199, v123, s[6:7]
	s_mov_b32 s40, 2
	s_and_b64 vcc, exec, s[6:7]
	s_waitcnt vmcnt(1)
	v_pk_mul_f32 v[2:3], v[114:115], v[114:115]
	s_nop 0
	v_sub_f32_e32 v2, v2, v3
	v_add_f32_e32 v3, v114, v114
	v_mul_f32_e32 v3, v115, v3
	v_mul_f32_e32 v4, v2, v2
	v_add_f32_e32 v2, v2, v2
	v_mul_f32_e32 v2, v3, v2
	v_fma_f32 v4, -v3, v3, v4
	v_mul_f32_e32 v3, v2, v2
	v_fma_f32 v3, v4, v4, -v3
	v_add_f32_e32 v4, v4, v4
	v_mul_f32_e32 v2, v2, v4
	v_mul_f32_e32 v4, v2, v2
	s_waitcnt vmcnt(0)
	v_pk_mul_f32 v[0:1], v[112:113], v[112:113]
	v_fma_f32 v230, v3, v3, -v4
	v_add_f32_e32 v3, v3, v3
	v_sub_f32_e32 v0, v0, v1
	v_add_f32_e32 v1, v112, v112
	v_mul_f32_e32 v231, v2, v3
	v_mul_f32_e32 v1, v113, v1
	v_mul_f32_e32 v2, v0, v0
	v_add_f32_e32 v0, v0, v0
	v_mul_f32_e32 v0, v1, v0
	v_fma_f32 v2, -v1, v1, v2
	v_mul_f32_e32 v1, v0, v0
	v_fma_f32 v1, v2, v2, -v1
	v_add_f32_e32 v2, v2, v2
	v_mul_f32_e32 v0, v0, v2
	v_mul_f32_e32 v2, v0, v0
	v_fma_f32 v228, v1, v1, -v2
	v_add_f32_e32 v1, v1, v1
	v_mul_f32_e32 v229, v0, v1
	v_lshl_add_u64 v[0:1], v[134:135], 0, s[38:39]
	s_or_b32 s38, s14, 1
	s_mov_b32 s39, s15
	s_lshl_b64 s[38:39], s[38:39], 10
	global_load_dwordx4 v[84:87], v[0:1], off
	v_lshl_add_u64 v[0:1], v[134:135], 0, s[38:39]
	s_or_b32 s38, s14, 2
	s_mov_b32 s39, s15
	s_lshl_b64 s[38:39], s[38:39], 10
	s_or_b32 s14, s14, 3
	global_load_dwordx4 v[88:91], v[0:1], off
	v_lshl_add_u64 v[0:1], v[134:135], 0, s[38:39]
	s_lshl_b64 s[38:39], s[14:15], 10
	s_lshl_b32 s14, s10, 4
	global_load_dwordx4 v[92:95], v[0:1], off
	v_lshl_add_u64 v[0:1], v[134:135], 0, s[38:39]
	v_or_b32_e32 v132, s14, v128
	global_load_dwordx4 v[96:99], v[0:1], off
	v_lshlrev_b64 v[0:1], 8, v[132:133]
	v_lshl_add_u64 v[0:1], v[138:139], 0, v[0:1]
	global_load_dwordx4 v[80:83], v[0:1], off
	global_load_dwordx4 v[76:79], v[0:1], off offset:64
	global_load_dwordx4 v[72:75], v[0:1], off offset:128
	global_load_dwordx4 v[68:71], v[0:1], off offset:192
	v_lshl_add_u64 v[0:1], s[14:15], 2, v[140:141]
	s_lshl_b32 s38, s10, 5
	s_mov_b32 s39, s15
	global_load_dwordx4 v[64:67], v[0:1], off
	v_lshl_add_u64 v[118:119], v[144:145], 0, s[38:39]
	v_or_b32_e32 v0, s14, v151
	v_lshl_add_u32 v132, v0, 1, s3
	v_lshl_add_u64 v[0:1], v[118:119], 0, v[100:101]
	global_load_dwordx4 v[0:3], v[0:1], off
	v_lshl_add_u64 v[116:117], v[146:147], 0, s[38:39]
	v_lshl_add_u64 v[244:245], v[118:119], 0, v[106:107]
	v_lshl_add_u64 v[248:249], v[116:117], 0, v[102:103]
	v_lshl_add_u64 v[250:251], v[116:117], 0, v[104:105]
	v_lshl_add_u64 v[252:253], v[116:117], 0, v[108:109]
	v_lshl_add_u64 v[242:243], v[116:117], 0, v[110:111]
	global_load_dwordx4 v[244:247], v[244:245], off
	global_load_dwordx2 v[248:249], v[248:249], off
	global_load_dwordx2 v[250:251], v[250:251], off
	global_load_dwordx2 v[252:253], v[252:253], off
	global_load_dwordx2 v[242:243], v[242:243], off
	s_or_b32 s38, s10, 1
	s_lshl_b32 s14, s38, 2
	s_lshl_b64 s[10:11], s[14:15], 10
	s_waitcnt vmcnt(0)
	v_mfma_f32_32x32x16_bf16 v[32:47], v[0:3], v[92:95], 0
	s_nop 11
	v_fma_f32 v237, 0, v115, v32
	v_mfma_f32_32x32x16_bf16 v[48:63], v[0:3], v[84:87], 0
	v_fmac_f32_e32 v237, 0, v114
	v_mfma_f32_32x32x16_bf16 v[16:31], v[0:3], v[88:91], 0
	s_nop 9
	v_fmamk_f32 v236, v115, 0x80000000, v48
	v_fmac_f32_e32 v236, 0, v114
	v_fma_f32 v238, -v115, v237, v49
	v_fmac_f32_e32 v238, v114, v236
	v_fma_f32 v236, v115, v236, v33
	v_fmac_f32_e32 v236, v114, v237
	v_fma_f32 v237, -v115, v236, v50
	v_fmac_f32_e32 v237, v114, v238
	v_fma_f32 v238, v115, v238, v34
	v_fmac_f32_e32 v238, v114, v236
	v_fma_f32 v236, -v115, v238, v51
	v_fmac_f32_e32 v236, v114, v237
	v_fma_f32 v237, v115, v237, v35
	v_fmac_f32_e32 v237, v114, v238
	v_fma_f32 v238, -v115, v237, v52
	v_fmac_f32_e32 v238, v114, v236
	v_fma_f32 v236, v115, v236, v36
	v_fmac_f32_e32 v236, v114, v237
	v_fma_f32 v237, -v115, v236, v53
	v_fmac_f32_e32 v237, v114, v238
	v_fma_f32 v238, v115, v238, v37
	v_fmac_f32_e32 v238, v114, v236
	v_fma_f32 v236, -v115, v238, v54
	v_fmac_f32_e32 v236, v114, v237
	v_fma_f32 v237, v115, v237, v38
	v_fmac_f32_e32 v237, v114, v238
	v_fma_f32 v238, -v115, v237, v55
	v_fmac_f32_e32 v238, v114, v236
	v_fma_f32 v236, v115, v236, v39
	v_fmac_f32_e32 v236, v114, v237
	v_fma_f32 v237, -v115, v236, v56
	v_fmac_f32_e32 v237, v114, v238
	v_fma_f32 v238, v115, v238, v40
	v_fmac_f32_e32 v238, v114, v236
	v_fma_f32 v236, -v115, v238, v57
	v_fmac_f32_e32 v236, v114, v237
	v_fma_f32 v237, v115, v237, v41
	v_fmac_f32_e32 v237, v114, v238
	v_fma_f32 v238, -v115, v237, v58
	v_fmac_f32_e32 v238, v114, v236
	v_fma_f32 v236, v115, v236, v42
	v_fmac_f32_e32 v236, v114, v237
	v_fma_f32 v237, -v115, v236, v59
	v_fmac_f32_e32 v237, v114, v238
	v_fma_f32 v238, v115, v238, v43
	v_fmac_f32_e32 v238, v114, v236
	v_fma_f32 v236, -v115, v238, v60
	v_fmac_f32_e32 v236, v114, v237
	v_fma_f32 v237, v115, v237, v44
	v_fmac_f32_e32 v237, v114, v238
	v_fma_f32 v238, -v115, v237, v61
	v_fmac_f32_e32 v238, v114, v236
	v_fma_f32 v236, v115, v236, v45
	v_fmac_f32_e32 v236, v114, v237
	v_fma_f32 v237, -v115, v236, v62
	v_fmac_f32_e32 v237, v114, v238
	v_fma_f32 v238, v115, v238, v46
	v_fmac_f32_e32 v238, v114, v236
	v_fma_f32 v236, -v115, v238, v63
	v_fmac_f32_e32 v236, v114, v237
	v_fma_f32 v237, v115, v237, v47
	v_fmac_f32_e32 v237, v114, v238
	ds_bpermute_b32 v238, v149, v236
	ds_bpermute_b32 v239, v149, v237
	v_mfma_f32_32x32x16_bf16 v[0:15], v[0:3], v[96:99], 0
	s_waitcnt lgkmcnt(1)
	v_cndmask_b32_e64 v240, v238, v236, s[0:1]
	s_waitcnt lgkmcnt(0)
	v_cndmask_b32_e64 v241, v239, v237, s[0:1]
	v_cndmask_b32_e64 v236, v236, v238, s[0:1]
	v_fma_f32 v238, -v231, v233, v240
	v_fmac_f32_e32 v241, v231, v232
	v_fmac_f32_e32 v238, v230, v232
	v_fmac_f32_e32 v241, v230, v233
	v_cndmask_b32_e64 v232, v238, v232, s[0:1]
	v_cndmask_b32_e64 v233, v241, v233, s[0:1]
	v_fma_f32 v48, -v115, v233, v48
	v_fma_f32 v32, v115, v232, v32
	v_fmac_f32_e32 v48, v114, v232
	v_fmac_f32_e32 v32, v114, v233
	v_fma_f32 v49, -v115, v32, v49
	v_fma_f32 v33, v115, v48, v33
	v_cvt_pk_bf16_f32 v232, v48, v32
	ds_write_b32 v137, v232
	v_fmac_f32_e32 v49, v114, v48
	v_fmac_f32_e32 v33, v114, v32
	v_cvt_pk_bf16_f32 v32, v49, v33
	ds_write_b32 v137, v32 offset:272
	v_fma_f32 v32, -v115, v33, v50
	v_fma_f32 v34, v115, v49, v34
	v_fmac_f32_e32 v32, v114, v49
	v_fmac_f32_e32 v34, v114, v33
	v_cvt_pk_bf16_f32 v33, v32, v34
	ds_write_b32 v137, v33 offset:544
	v_fma_f32 v33, -v115, v34, v51
	v_fmac_f32_e32 v33, v114, v32
	v_fma_f32 v32, v115, v32, v35
	v_fmac_f32_e32 v32, v114, v34
	v_cvt_pk_bf16_f32 v34, v33, v32
	ds_write_b32 v137, v34 offset:816
	v_fma_f32 v34, -v115, v32, v52
	v_fmac_f32_e32 v34, v114, v33
	v_fma_f32 v33, v115, v33, v36
	v_fmac_f32_e32 v33, v114, v32
	v_cvt_pk_bf16_f32 v32, v34, v33
	ds_write_b32 v137, v32 offset:1088
	v_fma_f32 v32, -v115, v33, v53
	v_fmac_f32_e32 v32, v114, v34
	v_fma_f32 v34, v115, v34, v37
	v_fmac_f32_e32 v34, v114, v33
	v_cvt_pk_bf16_f32 v33, v32, v34
	ds_write_b32 v137, v33 offset:1360
	v_fma_f32 v33, -v115, v34, v54
	v_fmac_f32_e32 v33, v114, v32
	v_fma_f32 v32, v115, v32, v38
	v_fmac_f32_e32 v32, v114, v34
	v_cvt_pk_bf16_f32 v34, v33, v32
	ds_write_b32 v137, v34 offset:1632
	v_fma_f32 v34, -v115, v32, v55
	v_fmac_f32_e32 v34, v114, v33
	v_fma_f32 v33, v115, v33, v39
	v_fmac_f32_e32 v33, v114, v32
	v_cvt_pk_bf16_f32 v32, v34, v33
	ds_write_b32 v137, v32 offset:1904
	v_fma_f32 v32, -v115, v33, v56
	v_fmac_f32_e32 v32, v114, v34
	v_fma_f32 v34, v115, v34, v40
	v_fmac_f32_e32 v34, v114, v33
	v_cvt_pk_bf16_f32 v33, v32, v34
	ds_write_b32 v137, v33 offset:2176
	v_fma_f32 v33, -v115, v34, v57
	v_fmac_f32_e32 v33, v114, v32
	v_fma_f32 v32, v115, v32, v41
	v_fmac_f32_e32 v32, v114, v34
	v_cvt_pk_bf16_f32 v34, v33, v32
	ds_write_b32 v137, v34 offset:2448
	v_fma_f32 v34, -v115, v32, v58
	v_fmac_f32_e32 v34, v114, v33
	v_fma_f32 v33, v115, v33, v42
	v_fmac_f32_e32 v33, v114, v32
	v_cvt_pk_bf16_f32 v32, v34, v33
	ds_write_b32 v137, v32 offset:2720
	v_fma_f32 v32, -v115, v33, v59
	v_fmac_f32_e32 v32, v114, v34
	v_fma_f32 v34, v115, v34, v43
	v_fmac_f32_e32 v34, v114, v33
	v_cvt_pk_bf16_f32 v33, v32, v34
	ds_write_b32 v137, v33 offset:2992
	v_fma_f32 v33, -v115, v34, v60
	v_fmac_f32_e32 v33, v114, v32
	v_fma_f32 v32, v115, v32, v44
	v_fmac_f32_e32 v32, v114, v34
	v_cvt_pk_bf16_f32 v34, v33, v32
	ds_write_b32 v137, v34 offset:3264
	v_fma_f32 v34, -v115, v32, v61
	v_fmac_f32_e32 v34, v114, v33
	v_fma_f32 v33, v115, v33, v45
	v_fmac_f32_e32 v33, v114, v32
	v_cvt_pk_bf16_f32 v32, v34, v33
	ds_write_b32 v137, v32 offset:3536
	v_fma_f32 v32, -v115, v33, v62
	v_fmac_f32_e32 v32, v114, v34
	v_fma_f32 v34, v115, v34, v46
	v_fmac_f32_e32 v34, v114, v33
	v_cvt_pk_bf16_f32 v33, v32, v34
	ds_write_b32 v137, v33 offset:3808
	v_fma_f32 v33, -v115, v34, v63
	v_fmac_f32_e32 v33, v114, v32
	v_fmac_f32_e32 v47, v115, v32
	v_fmac_f32_e32 v47, v114, v34
	v_cvt_pk_bf16_f32 v32, v33, v47
	v_fma_f32 v33, 0, v113, v0
	ds_write_b32 v137, v32 offset:4080
	v_fmamk_f32 v32, v113, 0x80000000, v16
	v_fmac_f32_e32 v33, 0, v112
	v_fmac_f32_e32 v32, 0, v112
	v_fma_f32 v34, -v113, v33, v17
	v_fmac_f32_e32 v34, v112, v32
	v_fma_f32 v32, v113, v32, v1
	v_fmac_f32_e32 v32, v112, v33
	v_fma_f32 v33, -v113, v32, v18
	v_fmac_f32_e32 v33, v112, v34
	v_fma_f32 v34, v113, v34, v2
	v_fmac_f32_e32 v34, v112, v32
	v_fma_f32 v32, -v113, v34, v19
	v_fmac_f32_e32 v32, v112, v33
	v_fma_f32 v33, v113, v33, v3
	v_fmac_f32_e32 v33, v112, v34
	v_fma_f32 v34, -v113, v33, v20
	v_fmac_f32_e32 v34, v112, v32
	v_fma_f32 v32, v113, v32, v4
	v_fmac_f32_e32 v32, v112, v33
	v_fma_f32 v33, -v113, v32, v21
	v_fmac_f32_e32 v33, v112, v34
	v_fma_f32 v34, v113, v34, v5
	v_fmac_f32_e32 v34, v112, v32
	v_fma_f32 v32, -v113, v34, v22
	v_fmac_f32_e32 v32, v112, v33
	v_fma_f32 v33, v113, v33, v6
	v_fmac_f32_e32 v33, v112, v34
	v_fma_f32 v34, -v113, v33, v23
	v_fmac_f32_e32 v34, v112, v32
	v_fma_f32 v32, v113, v32, v7
	v_fmac_f32_e32 v32, v112, v33
	v_fma_f32 v33, -v113, v32, v24
	v_fmac_f32_e32 v33, v112, v34
	v_fma_f32 v34, v113, v34, v8
	v_fmac_f32_e32 v34, v112, v32
	v_fma_f32 v32, -v113, v34, v25
	v_fmac_f32_e32 v32, v112, v33
	v_fma_f32 v33, v113, v33, v9
	v_fmac_f32_e32 v33, v112, v34
	v_fma_f32 v34, -v113, v33, v26
	v_fmac_f32_e32 v34, v112, v32
	v_fma_f32 v32, v113, v32, v10
	v_fmac_f32_e32 v32, v112, v33
	v_fma_f32 v33, -v113, v32, v27
	v_fmac_f32_e32 v33, v112, v34
	v_fma_f32 v34, v113, v34, v11
	v_fmac_f32_e32 v34, v112, v32
	v_fma_f32 v32, -v113, v34, v28
	v_fmac_f32_e32 v32, v112, v33
	v_fma_f32 v33, v113, v33, v12
	v_fmac_f32_e32 v33, v112, v34
	v_fma_f32 v34, -v113, v33, v29
	v_fmac_f32_e32 v34, v112, v32
	v_fma_f32 v32, v113, v32, v13
	v_fmac_f32_e32 v32, v112, v33
	v_fma_f32 v33, -v113, v32, v30
	v_fmac_f32_e32 v33, v112, v34
	v_fma_f32 v34, v113, v34, v14
	v_fmac_f32_e32 v34, v112, v32
	v_fma_f32 v32, -v113, v34, v31
	v_fmac_f32_e32 v32, v112, v33
	v_fma_f32 v33, v113, v33, v15
	v_fmac_f32_e32 v33, v112, v34
	ds_bpermute_b32 v34, v149, v32
	ds_bpermute_b32 v35, v149, v33
	v_cndmask_b32_e64 v237, v237, v239, s[0:1]
	v_fma_f32 v236, -v231, v241, v236
	v_fmac_f32_e32 v237, v231, v238
	s_waitcnt lgkmcnt(1)
	v_cndmask_b32_e64 v36, v34, v32, s[0:1]
	s_waitcnt lgkmcnt(0)
	v_cndmask_b32_e64 v37, v35, v33, s[0:1]
	v_cndmask_b32_e64 v232, v33, v35, s[0:1]
	v_fma_f32 v33, -v229, v235, v36
	v_fmac_f32_e32 v37, v229, v234
	v_fmac_f32_e32 v33, v228, v234
	v_fmac_f32_e32 v37, v228, v235
	v_cndmask_b32_e64 v32, v32, v34, s[0:1]
	v_cndmask_b32_e64 v34, v33, v234, s[0:1]
	v_cndmask_b32_e64 v35, v37, v235, s[0:1]
	v_fma_f32 v16, -v113, v35, v16
	v_fma_f32 v0, v113, v34, v0
	v_fmac_f32_e32 v16, v112, v34
	v_fmac_f32_e32 v0, v112, v35
	v_fma_f32 v17, -v113, v0, v17
	v_fma_f32 v1, v113, v16, v1
	v_fma_f32 v233, -v229, v37, v32
	v_cvt_pk_bf16_f32 v32, v16, v0
	ds_write_b32 v137, v32 offset:128
	v_fmac_f32_e32 v17, v112, v16
	v_fmac_f32_e32 v1, v112, v0
	v_cvt_pk_bf16_f32 v0, v17, v1
	ds_write_b32 v137, v0 offset:400
	v_fma_f32 v0, -v113, v1, v18
	v_fma_f32 v2, v113, v17, v2
	v_fmac_f32_e32 v0, v112, v17
	v_fmac_f32_e32 v2, v112, v1
	v_cvt_pk_bf16_f32 v1, v0, v2
	ds_write_b32 v137, v1 offset:672
	v_fma_f32 v1, -v113, v2, v19
	v_fmac_f32_e32 v1, v112, v0
	v_fma_f32 v0, v113, v0, v3
	v_fmac_f32_e32 v0, v112, v2
	v_cvt_pk_bf16_f32 v2, v1, v0
	ds_write_b32 v137, v2 offset:944
	v_fma_f32 v2, -v113, v0, v20
	v_fmac_f32_e32 v2, v112, v1
	v_fma_f32 v1, v113, v1, v4
	v_fmac_f32_e32 v1, v112, v0
	v_cvt_pk_bf16_f32 v0, v2, v1
	ds_write_b32 v137, v0 offset:1216
	v_fma_f32 v0, -v113, v1, v21
	v_fmac_f32_e32 v0, v112, v2
	v_fma_f32 v2, v113, v2, v5
	v_fmac_f32_e32 v2, v112, v1
	v_cvt_pk_bf16_f32 v1, v0, v2
	ds_write_b32 v137, v1 offset:1488
	v_fma_f32 v1, -v113, v2, v22
	v_fmac_f32_e32 v1, v112, v0
	v_fma_f32 v0, v113, v0, v6
	v_fmac_f32_e32 v0, v112, v2
	v_cvt_pk_bf16_f32 v2, v1, v0
	ds_write_b32 v137, v2 offset:1760
	v_fma_f32 v2, -v113, v0, v23
	v_fmac_f32_e32 v2, v112, v1
	v_fma_f32 v1, v113, v1, v7
	v_fmac_f32_e32 v1, v112, v0
	v_cvt_pk_bf16_f32 v0, v2, v1
	ds_write_b32 v137, v0 offset:2032
	v_fma_f32 v0, -v113, v1, v24
	v_fmac_f32_e32 v0, v112, v2
	v_fma_f32 v2, v113, v2, v8
	v_fmac_f32_e32 v2, v112, v1
	v_cvt_pk_bf16_f32 v1, v0, v2
	ds_write_b32 v137, v1 offset:2304
	v_fma_f32 v1, -v113, v2, v25
	v_fmac_f32_e32 v1, v112, v0
	v_fma_f32 v0, v113, v0, v9
	v_fmac_f32_e32 v0, v112, v2
	v_cvt_pk_bf16_f32 v2, v1, v0
	ds_write_b32 v137, v2 offset:2576
	v_fma_f32 v2, -v113, v0, v26
	v_fmac_f32_e32 v2, v112, v1
	v_fma_f32 v1, v113, v1, v10
	v_fmac_f32_e32 v1, v112, v0
	v_cvt_pk_bf16_f32 v0, v2, v1
	ds_write_b32 v137, v0 offset:2848
	v_fma_f32 v0, -v113, v1, v27
	v_fmac_f32_e32 v0, v112, v2
	v_fma_f32 v2, v113, v2, v11
	v_fmac_f32_e32 v2, v112, v1
	v_cvt_pk_bf16_f32 v1, v0, v2
	ds_write_b32 v137, v1 offset:3120
	v_fma_f32 v1, -v113, v2, v28
	v_fmac_f32_e32 v1, v112, v0
	v_fma_f32 v0, v113, v0, v12
	v_fmac_f32_e32 v0, v112, v2
	v_cvt_pk_bf16_f32 v2, v1, v0
	ds_write_b32 v137, v2 offset:3392
	v_fma_f32 v2, -v113, v0, v29
	v_fmac_f32_e32 v2, v112, v1
	v_fma_f32 v1, v113, v1, v13
	v_fmac_f32_e32 v1, v112, v0
	v_cvt_pk_bf16_f32 v0, v2, v1
	ds_write_b32 v137, v0 offset:3664
	v_fma_f32 v0, -v113, v1, v30
	v_fmac_f32_e32 v0, v112, v2
	v_fma_f32 v2, v113, v2, v14
	v_fmac_f32_e32 v2, v112, v1
	v_cvt_pk_bf16_f32 v1, v0, v2
	ds_write_b32 v137, v1 offset:3936
	v_fma_f32 v1, -v113, v2, v31
	v_fmac_f32_e32 v15, v113, v0
	v_fmac_f32_e32 v1, v112, v0
	v_fmac_f32_e32 v15, v112, v2
	v_cvt_pk_bf16_f32 v0, v1, v15
	ds_write_b32 v137, v0 offset:4208
	ds_read_b128 v[0:3], v220
	ds_read_b128 v[4:7], v220 offset:64
	ds_read_b128 v[8:11], v220 offset:128
	ds_read_b128 v[16:19], v220 offset:192
	s_waitcnt lgkmcnt(3)
	v_mfma_f32_16x16x32_bf16 v[0:3], v[80:83], v[0:3], 0
	v_add_u32_e32 v234, v132, v153
	v_fmac_f32_e32 v232, v229, v33
	v_fmac_f32_e32 v233, v228, v33
	s_waitcnt lgkmcnt(2)
	v_mfma_f32_16x16x32_bf16 v[0:3], v[76:79], v[4:7], v[0:3]
	v_fmac_f32_e32 v232, v228, v37
	v_fmac_f32_e32 v236, v230, v238
	s_waitcnt lgkmcnt(1)
	v_mfma_f32_16x16x32_bf16 v[0:3], v[72:75], v[8:11], v[0:3]
	v_fmac_f32_e32 v237, v230, v241
	s_waitcnt lgkmcnt(0)
	v_mfma_f32_16x16x32_bf16 v[0:3], v[68:71], v[16:19], v[0:3]
	v_mov_b64_e32 v[4:5], v[248:249]
	s_nop 1
	v_lshlrev_b32_e32 v6, 16, v4
	v_and_b32_e32 v4, 0xffff0000, v4
	s_nop 2
	v_fma_f32 v1, v65, v4, v1
	v_mul_f32_e32 v4, 0x3d372713, v1
	v_mul_f32_e32 v4, v1, v4
	v_fma_f32 v4, v1, v4, v1
	v_mul_f32_e32 v4, 0x3f4c422a, v4
	v_add_f32_e32 v4, v4, v4
	v_mul_f32_e32 v4, 0x3fb8aa3b, v4
	v_exp_f32_e32 v4, v4
	v_fma_f32 v0, v64, v6, v0
	v_mul_f32_e32 v6, 0x3d372713, v0
	v_mul_f32_e32 v6, v0, v6
	v_add_f32_e32 v4, 1.0, v4
	v_rcp_f32_e32 v4, v4
	v_fma_f32 v6, v0, v6, v0
	v_mul_f32_e32 v6, 0x3f4c422a, v6
	v_add_f32_e32 v6, v6, v6
	v_sub_f32_e32 v4, 1.0, v4
	v_mul_f32_e32 v1, v1, v4
	v_lshlrev_b32_e32 v4, 16, v5
	v_fma_f32 v2, v66, v4, v2
	v_mul_f32_e32 v4, 0x3d372713, v2
	v_mul_f32_e32 v4, v2, v4
	v_fma_f32 v4, v2, v4, v2
	v_mul_f32_e32 v4, 0x3f4c422a, v4
	v_add_f32_e32 v4, v4, v4
	v_mul_f32_e32 v4, 0x3fb8aa3b, v4
	v_exp_f32_e32 v4, v4
	v_mul_f32_e32 v6, 0x3fb8aa3b, v6
	v_exp_f32_e32 v6, v6
	v_add_f32_e32 v4, 1.0, v4
	v_rcp_f32_e32 v4, v4
	v_add_f32_e32 v6, 1.0, v6
	v_rcp_f32_e32 v6, v6
	v_sub_f32_e32 v4, 1.0, v4
	v_mul_f32_e32 v2, v2, v4
	v_and_b32_e32 v4, 0xffff0000, v5
	v_fmac_f32_e32 v3, v67, v4
	v_mul_f32_e32 v4, 0x3d372713, v3
	v_mul_f32_e32 v4, v3, v4
	v_fma_f32 v4, v3, v4, v3
	v_mul_f32_e32 v4, 0x3f4c422a, v4
	v_add_f32_e32 v4, v4, v4
	v_mul_f32_e32 v4, 0x3fb8aa3b, v4
	v_exp_f32_e32 v4, v4
	v_sub_f32_e32 v6, 1.0, v6
	v_mul_f32_e32 v0, v0, v6
	v_cvt_pk_bf16_f32 v0, v0, v1
	v_add_f32_e32 v4, 1.0, v4
	v_rcp_f32_e32 v4, v4
	s_nop 0
	v_sub_f32_e32 v4, 1.0, v4
	v_mul_f32_e32 v3, v3, v4
	v_cvt_pk_bf16_f32 v1, v2, v3
	ds_write_b64 v234, v[0:1]
	ds_read_b128 v[0:3], v220 offset:4352
	ds_read_b128 v[4:7], v220 offset:4416
	ds_read_b128 v[8:11], v220 offset:4480
	ds_read_b128 v[16:19], v220 offset:4544
	s_waitcnt lgkmcnt(3)
	v_mfma_f32_16x16x32_bf16 v[0:3], v[80:83], v[0:3], 0
	s_waitcnt lgkmcnt(2)
	v_mfma_f32_16x16x32_bf16 v[0:3], v[76:79], v[4:7], v[0:3]
	s_waitcnt lgkmcnt(1)
	v_mfma_f32_16x16x32_bf16 v[0:3], v[72:75], v[8:11], v[0:3]
	s_waitcnt lgkmcnt(0)
	v_mfma_f32_16x16x32_bf16 v[0:3], v[68:71], v[16:19], v[0:3]
	v_mov_b64_e32 v[4:5], v[250:251]
	s_nop 1
	v_lshlrev_b32_e32 v6, 16, v4
	v_and_b32_e32 v4, 0xffff0000, v4
	s_nop 2
	v_fma_f32 v1, v65, v4, v1
	v_mul_f32_e32 v4, 0x3d372713, v1
	v_mul_f32_e32 v4, v1, v4
	v_fma_f32 v4, v1, v4, v1
	v_mul_f32_e32 v4, 0x3f4c422a, v4
	v_add_f32_e32 v4, v4, v4
	v_mul_f32_e32 v4, 0x3fb8aa3b, v4
	v_exp_f32_e32 v4, v4
	v_fma_f32 v0, v64, v6, v0
	v_mul_f32_e32 v6, 0x3d372713, v0
	v_mul_f32_e32 v6, v0, v6
	v_add_f32_e32 v4, 1.0, v4
	v_rcp_f32_e32 v4, v4
	v_fma_f32 v6, v0, v6, v0
	v_mul_f32_e32 v6, 0x3f4c422a, v6
	v_add_f32_e32 v6, v6, v6
	v_sub_f32_e32 v4, 1.0, v4
	v_mul_f32_e32 v1, v1, v4
	v_lshlrev_b32_e32 v4, 16, v5
	v_fma_f32 v2, v66, v4, v2
	v_mul_f32_e32 v4, 0x3d372713, v2
	v_mul_f32_e32 v4, v2, v4
	v_fma_f32 v4, v2, v4, v2
	v_mul_f32_e32 v4, 0x3f4c422a, v4
	v_add_f32_e32 v4, v4, v4
	v_mul_f32_e32 v4, 0x3fb8aa3b, v4
	v_exp_f32_e32 v4, v4
	v_mul_f32_e32 v6, 0x3fb8aa3b, v6
	v_exp_f32_e32 v6, v6
	v_add_f32_e32 v4, 1.0, v4
	v_rcp_f32_e32 v4, v4
	v_add_f32_e32 v6, 1.0, v6
	v_rcp_f32_e32 v6, v6
	v_sub_f32_e32 v4, 1.0, v4
	v_mul_f32_e32 v2, v2, v4
	v_and_b32_e32 v4, 0xffff0000, v5
	v_fmac_f32_e32 v3, v67, v4
	v_mul_f32_e32 v4, 0x3d372713, v3
	v_mul_f32_e32 v4, v3, v4
	v_fma_f32 v4, v3, v4, v3
	v_mul_f32_e32 v4, 0x3f4c422a, v4
	v_add_f32_e32 v4, v4, v4
	v_mul_f32_e32 v4, 0x3fb8aa3b, v4
	v_exp_f32_e32 v4, v4
	v_sub_f32_e32 v6, 1.0, v6
	v_mul_f32_e32 v0, v0, v6
	v_cvt_pk_bf16_f32 v0, v0, v1
	v_add_f32_e32 v4, 1.0, v4
	v_rcp_f32_e32 v4, v4
	s_nop 0
	v_sub_f32_e32 v4, 1.0, v4
	v_mul_f32_e32 v3, v3, v4
	v_cvt_pk_bf16_f32 v1, v2, v3
	ds_write_b64 v234, v[0:1] offset:16640
	v_mfma_f32_32x32x16_bf16 v[32:47], v[244:247], v[92:95], 0
	v_mfma_f32_32x32x16_bf16 v[48:63], v[244:247], v[84:87], 0
	s_nop 10
	v_fma_f32 v85, 0, v115, v32
	v_fmac_f32_e32 v85, 0, v114
	v_mfma_f32_32x32x16_bf16 v[16:31], v[244:247], v[88:91], 0
	v_fmamk_f32 v84, v115, 0x80000000, v48
	v_fmac_f32_e32 v84, 0, v114
	v_fma_f32 v86, -v115, v85, v49
	v_fmac_f32_e32 v86, v114, v84
	v_fma_f32 v84, v115, v84, v33
	v_fmac_f32_e32 v84, v114, v85
	v_fma_f32 v85, -v115, v84, v50
	v_fmac_f32_e32 v85, v114, v86
	v_fma_f32 v86, v115, v86, v34
	v_fmac_f32_e32 v86, v114, v84
	v_fma_f32 v84, -v115, v86, v51
	v_fmac_f32_e32 v84, v114, v85
	v_fma_f32 v85, v115, v85, v35
	v_fmac_f32_e32 v85, v114, v86
	v_fma_f32 v86, -v115, v85, v52
	v_fmac_f32_e32 v86, v114, v84
	v_fma_f32 v84, v115, v84, v36
	v_fmac_f32_e32 v84, v114, v85
	v_fma_f32 v85, -v115, v84, v53
	v_fmac_f32_e32 v85, v114, v86
	v_fma_f32 v86, v115, v86, v37
	v_fmac_f32_e32 v86, v114, v84
	v_fma_f32 v84, -v115, v86, v54
	v_fmac_f32_e32 v84, v114, v85
	v_fma_f32 v85, v115, v85, v38
	v_fmac_f32_e32 v85, v114, v86
	v_fma_f32 v86, -v115, v85, v55
	v_fmac_f32_e32 v86, v114, v84
	v_fma_f32 v84, v115, v84, v39
	v_fmac_f32_e32 v84, v114, v85
	v_fma_f32 v85, -v115, v84, v56
	v_fmac_f32_e32 v85, v114, v86
	v_fma_f32 v86, v115, v86, v40
	v_fmac_f32_e32 v86, v114, v84
	v_fma_f32 v84, -v115, v86, v57
	v_fmac_f32_e32 v84, v114, v85
	v_fma_f32 v85, v115, v85, v41
	v_fmac_f32_e32 v85, v114, v86
	v_fma_f32 v86, -v115, v85, v58
	v_fmac_f32_e32 v86, v114, v84
	v_fma_f32 v84, v115, v84, v42
	v_fmac_f32_e32 v84, v114, v85
	v_fma_f32 v85, -v115, v84, v59
	v_fmac_f32_e32 v85, v114, v86
	v_fma_f32 v86, v115, v86, v43
	v_fmac_f32_e32 v86, v114, v84
	v_fma_f32 v84, -v115, v86, v60
	v_fmac_f32_e32 v84, v114, v85
	v_fma_f32 v85, v115, v85, v44
	v_fmac_f32_e32 v85, v114, v86
	v_fma_f32 v86, -v115, v85, v61
	v_fmac_f32_e32 v86, v114, v84
	v_fma_f32 v84, v115, v84, v45
	v_fmac_f32_e32 v84, v114, v85
	v_fma_f32 v85, -v115, v84, v62
	v_fmac_f32_e32 v85, v114, v86
	v_fma_f32 v86, v115, v86, v46
	v_fmac_f32_e32 v86, v114, v84
	v_fma_f32 v84, -v115, v86, v63
	v_fmac_f32_e32 v84, v114, v85
	v_fma_f32 v85, v115, v85, v47
	v_fmac_f32_e32 v85, v114, v86
	ds_bpermute_b32 v86, v149, v84
	ds_bpermute_b32 v87, v149, v85
	v_mfma_f32_32x32x16_bf16 v[0:15], v[244:247], v[96:99], 0
	s_waitcnt lgkmcnt(1)
	v_cndmask_b32_e64 v84, v86, v84, s[0:1]
	s_waitcnt lgkmcnt(0)
	v_cndmask_b32_e64 v85, v87, v85, s[0:1]
	v_fma_f32 v84, -v231, v237, v84
	v_fmac_f32_e32 v85, v231, v236
	v_fmac_f32_e32 v84, v230, v236
	v_fmac_f32_e32 v85, v230, v237
	v_cndmask_b32_e64 v84, v84, v236, s[0:1]
	v_cndmask_b32_e64 v85, v85, v237, s[0:1]
	v_fma_f32 v48, -v115, v85, v48
	v_fma_f32 v32, v115, v84, v32
	v_fmac_f32_e32 v48, v114, v84
	v_fmac_f32_e32 v32, v114, v85
	v_fma_f32 v49, -v115, v32, v49
	v_fma_f32 v33, v115, v48, v33
	v_cvt_pk_bf16_f32 v84, v48, v32
	ds_write_b32 v137, v84
	v_fmac_f32_e32 v49, v114, v48
	v_fmac_f32_e32 v33, v114, v32
	v_cvt_pk_bf16_f32 v32, v49, v33
	ds_write_b32 v137, v32 offset:272
	v_fma_f32 v32, -v115, v33, v50
	v_fma_f32 v34, v115, v49, v34
	v_fmac_f32_e32 v32, v114, v49
	v_fmac_f32_e32 v34, v114, v33
	v_cvt_pk_bf16_f32 v33, v32, v34
	ds_write_b32 v137, v33 offset:544
	v_fma_f32 v33, -v115, v34, v51
	v_fmac_f32_e32 v33, v114, v32
	v_fma_f32 v32, v115, v32, v35
	v_fmac_f32_e32 v32, v114, v34
	v_cvt_pk_bf16_f32 v34, v33, v32
	ds_write_b32 v137, v34 offset:816
	v_fma_f32 v34, -v115, v32, v52
	v_fmac_f32_e32 v34, v114, v33
	v_fma_f32 v33, v115, v33, v36
	v_fmac_f32_e32 v33, v114, v32
	v_cvt_pk_bf16_f32 v32, v34, v33
	ds_write_b32 v137, v32 offset:1088
	v_fma_f32 v32, -v115, v33, v53
	v_fmac_f32_e32 v32, v114, v34
	v_fma_f32 v34, v115, v34, v37
	v_fmac_f32_e32 v34, v114, v33
	v_cvt_pk_bf16_f32 v33, v32, v34
	ds_write_b32 v137, v33 offset:1360
	v_fma_f32 v33, -v115, v34, v54
	v_fmac_f32_e32 v33, v114, v32
	v_fma_f32 v32, v115, v32, v38
	v_fmac_f32_e32 v32, v114, v34
	v_cvt_pk_bf16_f32 v34, v33, v32
	ds_write_b32 v137, v34 offset:1632
	v_fma_f32 v34, -v115, v32, v55
	v_fmac_f32_e32 v34, v114, v33
	v_fma_f32 v33, v115, v33, v39
	v_fmac_f32_e32 v33, v114, v32
	v_cvt_pk_bf16_f32 v32, v34, v33
	ds_write_b32 v137, v32 offset:1904
	v_fma_f32 v32, -v115, v33, v56
	v_fmac_f32_e32 v32, v114, v34
	v_fma_f32 v34, v115, v34, v40
	v_fmac_f32_e32 v34, v114, v33
	v_cvt_pk_bf16_f32 v33, v32, v34
	ds_write_b32 v137, v33 offset:2176
	v_fma_f32 v33, -v115, v34, v57
	v_fmac_f32_e32 v33, v114, v32
	v_fma_f32 v32, v115, v32, v41
	v_fmac_f32_e32 v32, v114, v34
	v_cvt_pk_bf16_f32 v34, v33, v32
	ds_write_b32 v137, v34 offset:2448
	v_fma_f32 v34, -v115, v32, v58
	v_fmac_f32_e32 v34, v114, v33
	v_fma_f32 v33, v115, v33, v42
	v_fmac_f32_e32 v33, v114, v32
	v_cvt_pk_bf16_f32 v32, v34, v33
	ds_write_b32 v137, v32 offset:2720
	v_fma_f32 v32, -v115, v33, v59
	v_fmac_f32_e32 v32, v114, v34
	v_fma_f32 v34, v115, v34, v43
	v_fmac_f32_e32 v34, v114, v33
	v_cvt_pk_bf16_f32 v33, v32, v34
	ds_write_b32 v137, v33 offset:2992
	v_fma_f32 v33, -v115, v34, v60
	v_fmac_f32_e32 v33, v114, v32
	v_fma_f32 v32, v115, v32, v44
	v_fmac_f32_e32 v32, v114, v34
	v_cvt_pk_bf16_f32 v34, v33, v32
	ds_write_b32 v137, v34 offset:3264
	v_fma_f32 v34, -v115, v32, v61
	v_fmac_f32_e32 v34, v114, v33
	v_fma_f32 v33, v115, v33, v45
	v_fmac_f32_e32 v33, v114, v32
	v_cvt_pk_bf16_f32 v32, v34, v33
	ds_write_b32 v137, v32 offset:3536
	v_fma_f32 v32, -v115, v33, v62
	v_fmac_f32_e32 v32, v114, v34
	v_fma_f32 v34, v115, v34, v46
	v_fmac_f32_e32 v34, v114, v33
	v_cvt_pk_bf16_f32 v33, v32, v34
	ds_write_b32 v137, v33 offset:3808
	v_fma_f32 v33, -v115, v34, v63
	v_fmac_f32_e32 v33, v114, v32
	v_fmac_f32_e32 v47, v115, v32
	v_fmac_f32_e32 v47, v114, v34
	v_cvt_pk_bf16_f32 v32, v33, v47
	v_fma_f32 v33, 0, v113, v0
	ds_write_b32 v137, v32 offset:4080
	v_fmamk_f32 v32, v113, 0x80000000, v16
	v_fmac_f32_e32 v33, 0, v112
	v_fmac_f32_e32 v32, 0, v112
	v_fma_f32 v34, -v113, v33, v17
	v_fmac_f32_e32 v34, v112, v32
	v_fma_f32 v32, v113, v32, v1
	v_fmac_f32_e32 v32, v112, v33
	v_fma_f32 v33, -v113, v32, v18
	v_fmac_f32_e32 v33, v112, v34
	v_fma_f32 v34, v113, v34, v2
	v_fmac_f32_e32 v34, v112, v32
	v_fma_f32 v32, -v113, v34, v19
	v_fmac_f32_e32 v32, v112, v33
	v_fma_f32 v33, v113, v33, v3
	v_fmac_f32_e32 v33, v112, v34
	v_fma_f32 v34, -v113, v33, v20
	v_fmac_f32_e32 v34, v112, v32
	v_fma_f32 v32, v113, v32, v4
	v_fmac_f32_e32 v32, v112, v33
	v_fma_f32 v33, -v113, v32, v21
	v_fmac_f32_e32 v33, v112, v34
	v_fma_f32 v34, v113, v34, v5
	v_fmac_f32_e32 v34, v112, v32
	v_fma_f32 v32, -v113, v34, v22
	v_fmac_f32_e32 v32, v112, v33
	v_fma_f32 v33, v113, v33, v6
	v_fmac_f32_e32 v33, v112, v34
	v_fma_f32 v34, -v113, v33, v23
	v_fmac_f32_e32 v34, v112, v32
	v_fma_f32 v32, v113, v32, v7
	v_fmac_f32_e32 v32, v112, v33
	v_fma_f32 v33, -v113, v32, v24
	v_fmac_f32_e32 v33, v112, v34
	v_fma_f32 v34, v113, v34, v8
	v_fmac_f32_e32 v34, v112, v32
	v_fma_f32 v32, -v113, v34, v25
	v_fmac_f32_e32 v32, v112, v33
	v_fma_f32 v33, v113, v33, v9
	v_fmac_f32_e32 v33, v112, v34
	v_fma_f32 v34, -v113, v33, v26
	v_fmac_f32_e32 v34, v112, v32
	v_fma_f32 v32, v113, v32, v10
	v_fmac_f32_e32 v32, v112, v33
	v_fma_f32 v33, -v113, v32, v27
	v_fmac_f32_e32 v33, v112, v34
	v_fma_f32 v34, v113, v34, v11
	v_fmac_f32_e32 v34, v112, v32
	v_fma_f32 v32, -v113, v34, v28
	v_fmac_f32_e32 v32, v112, v33
	v_fma_f32 v33, v113, v33, v12
	v_fmac_f32_e32 v33, v112, v34
	v_fma_f32 v34, -v113, v33, v29
	v_fmac_f32_e32 v34, v112, v32
	v_fma_f32 v32, v113, v32, v13
	v_fmac_f32_e32 v32, v112, v33
	v_fma_f32 v33, -v113, v32, v30
	v_fmac_f32_e32 v33, v112, v34
	v_fma_f32 v34, v113, v34, v14
	v_fmac_f32_e32 v34, v112, v32
	v_fma_f32 v32, -v113, v34, v31
	v_fmac_f32_e32 v32, v112, v33
	v_fma_f32 v33, v113, v33, v15
	v_fmac_f32_e32 v33, v112, v34
	ds_bpermute_b32 v34, v149, v32
	ds_bpermute_b32 v35, v149, v33
	v_cndmask_b32_e64 v236, v226, v126, s[6:7]
	v_cndmask_b32_e64 v237, v227, v127, s[6:7]
	s_waitcnt lgkmcnt(1)
	v_cndmask_b32_e64 v32, v34, v32, s[0:1]
	s_waitcnt lgkmcnt(0)
	v_cndmask_b32_e64 v33, v35, v33, s[0:1]
	v_fma_f32 v32, -v229, v232, v32
	v_fmac_f32_e32 v33, v229, v233
	v_fmac_f32_e32 v32, v228, v233
	v_fmac_f32_e32 v33, v228, v232
	v_cndmask_b32_e64 v32, v32, v233, s[0:1]
	v_cndmask_b32_e64 v33, v33, v232, s[0:1]
	v_fma_f32 v16, -v113, v33, v16
	v_fma_f32 v0, v113, v32, v0
	v_fmac_f32_e32 v16, v112, v32
	v_fmac_f32_e32 v0, v112, v33
	v_fma_f32 v17, -v113, v0, v17
	v_fma_f32 v1, v113, v16, v1
	v_cvt_pk_bf16_f32 v32, v16, v0
	ds_write_b32 v137, v32 offset:128
	v_fmac_f32_e32 v17, v112, v16
	v_fmac_f32_e32 v1, v112, v0
	v_cvt_pk_bf16_f32 v0, v17, v1
	ds_write_b32 v137, v0 offset:400
	v_fma_f32 v0, -v113, v1, v18
	v_fma_f32 v2, v113, v17, v2
	v_fmac_f32_e32 v0, v112, v17
	v_fmac_f32_e32 v2, v112, v1
	v_cvt_pk_bf16_f32 v1, v0, v2
	ds_write_b32 v137, v1 offset:672
	v_fma_f32 v1, -v113, v2, v19
	v_fmac_f32_e32 v1, v112, v0
	v_fma_f32 v0, v113, v0, v3
	v_fmac_f32_e32 v0, v112, v2
	v_cvt_pk_bf16_f32 v2, v1, v0
	ds_write_b32 v137, v2 offset:944
	v_fma_f32 v2, -v113, v0, v20
	v_fmac_f32_e32 v2, v112, v1
	v_fma_f32 v1, v113, v1, v4
	v_fmac_f32_e32 v1, v112, v0
	v_cvt_pk_bf16_f32 v0, v2, v1
	ds_write_b32 v137, v0 offset:1216
	v_fma_f32 v0, -v113, v1, v21
	v_fmac_f32_e32 v0, v112, v2
	v_fma_f32 v2, v113, v2, v5
	v_fmac_f32_e32 v2, v112, v1
	v_cvt_pk_bf16_f32 v1, v0, v2
	ds_write_b32 v137, v1 offset:1488
	v_fma_f32 v1, -v113, v2, v22
	v_fmac_f32_e32 v1, v112, v0
	v_fma_f32 v0, v113, v0, v6
	v_fmac_f32_e32 v0, v112, v2
	v_cvt_pk_bf16_f32 v2, v1, v0
	ds_write_b32 v137, v2 offset:1760
	v_fma_f32 v2, -v113, v0, v23
	v_fmac_f32_e32 v2, v112, v1
	v_fma_f32 v1, v113, v1, v7
	v_fmac_f32_e32 v1, v112, v0
	v_cvt_pk_bf16_f32 v0, v2, v1
	ds_write_b32 v137, v0 offset:2032
	v_fma_f32 v0, -v113, v1, v24
	v_fmac_f32_e32 v0, v112, v2
	v_fma_f32 v2, v113, v2, v8
	v_fmac_f32_e32 v2, v112, v1
	v_cvt_pk_bf16_f32 v1, v0, v2
	ds_write_b32 v137, v1 offset:2304
	v_fma_f32 v1, -v113, v2, v25
	v_fmac_f32_e32 v1, v112, v0
	v_fma_f32 v0, v113, v0, v9
	v_fmac_f32_e32 v0, v112, v2
	v_cvt_pk_bf16_f32 v2, v1, v0
	ds_write_b32 v137, v2 offset:2576
	v_fma_f32 v2, -v113, v0, v26
	v_fmac_f32_e32 v2, v112, v1
	v_fma_f32 v1, v113, v1, v10
	v_fmac_f32_e32 v1, v112, v0
	v_cvt_pk_bf16_f32 v0, v2, v1
	ds_write_b32 v137, v0 offset:2848
	v_fma_f32 v0, -v113, v1, v27
	v_fmac_f32_e32 v0, v112, v2
	v_fma_f32 v2, v113, v2, v11
	v_fmac_f32_e32 v2, v112, v1
	v_cvt_pk_bf16_f32 v1, v0, v2
	ds_write_b32 v137, v1 offset:3120
	v_fma_f32 v1, -v113, v2, v28
	v_fmac_f32_e32 v1, v112, v0
	v_fma_f32 v0, v113, v0, v12
	v_fmac_f32_e32 v0, v112, v2
	v_cvt_pk_bf16_f32 v2, v1, v0
	ds_write_b32 v137, v2 offset:3392
	v_fma_f32 v2, -v113, v0, v29
	v_fmac_f32_e32 v2, v112, v1
	v_fma_f32 v1, v113, v1, v13
	v_fmac_f32_e32 v1, v112, v0
	v_cvt_pk_bf16_f32 v0, v2, v1
	ds_write_b32 v137, v0 offset:3664
	v_fma_f32 v0, -v113, v1, v30
	v_fmac_f32_e32 v0, v112, v2
	v_fma_f32 v2, v113, v2, v14
	v_fmac_f32_e32 v2, v112, v1
	v_cvt_pk_bf16_f32 v1, v0, v2
	ds_write_b32 v137, v1 offset:3936
	v_fma_f32 v1, -v113, v2, v31
	v_fmac_f32_e32 v15, v113, v0
	v_fmac_f32_e32 v1, v112, v0
	v_fmac_f32_e32 v15, v112, v2
	v_cvt_pk_bf16_f32 v0, v1, v15
	ds_write_b32 v137, v0 offset:4208
	ds_read_b128 v[0:3], v220
	ds_read_b128 v[4:7], v220 offset:64
	ds_read_b128 v[8:11], v220 offset:128
	ds_read_b128 v[16:19], v220 offset:192
	s_waitcnt lgkmcnt(3)
	v_mfma_f32_16x16x32_bf16 v[0:3], v[80:83], v[0:3], 0
	v_cndmask_b32_e64 v232, v224, v124, s[6:7]
	v_cndmask_b32_e64 v233, v225, v125, s[6:7]
	s_mov_b64 s[6:7], 0
	s_waitcnt lgkmcnt(2)
	v_mfma_f32_16x16x32_bf16 v[0:3], v[76:79], v[4:7], v[0:3]
	s_waitcnt lgkmcnt(1)
	v_mfma_f32_16x16x32_bf16 v[0:3], v[72:75], v[8:11], v[0:3]
	s_waitcnt lgkmcnt(0)
	v_mfma_f32_16x16x32_bf16 v[0:3], v[68:71], v[16:19], v[0:3]
	v_mov_b64_e32 v[4:5], v[252:253]
	s_nop 1
	v_lshlrev_b32_e32 v6, 16, v4
	v_and_b32_e32 v4, 0xffff0000, v4
	s_nop 2
	v_fma_f32 v1, v65, v4, v1
	v_mul_f32_e32 v4, 0x3d372713, v1
	v_mul_f32_e32 v4, v1, v4
	v_fma_f32 v4, v1, v4, v1
	v_mul_f32_e32 v4, 0x3f4c422a, v4
	v_add_f32_e32 v4, v4, v4
	v_mul_f32_e32 v4, 0x3fb8aa3b, v4
	v_exp_f32_e32 v4, v4
	v_fma_f32 v0, v64, v6, v0
	v_mul_f32_e32 v6, 0x3d372713, v0
	v_mul_f32_e32 v6, v0, v6
	v_add_f32_e32 v4, 1.0, v4
	v_rcp_f32_e32 v4, v4
	v_fma_f32 v6, v0, v6, v0
	v_mul_f32_e32 v6, 0x3f4c422a, v6
	v_add_f32_e32 v6, v6, v6
	v_sub_f32_e32 v4, 1.0, v4
	v_mul_f32_e32 v1, v1, v4
	v_lshlrev_b32_e32 v4, 16, v5
	v_fma_f32 v2, v66, v4, v2
	v_mul_f32_e32 v4, 0x3d372713, v2
	v_mul_f32_e32 v4, v2, v4
	v_fma_f32 v4, v2, v4, v2
	v_mul_f32_e32 v4, 0x3f4c422a, v4
	v_add_f32_e32 v4, v4, v4
	v_mul_f32_e32 v4, 0x3fb8aa3b, v4
	v_exp_f32_e32 v4, v4
	v_mul_f32_e32 v6, 0x3fb8aa3b, v6
	v_exp_f32_e32 v6, v6
	v_add_f32_e32 v4, 1.0, v4
	v_rcp_f32_e32 v4, v4
	v_add_f32_e32 v6, 1.0, v6
	v_rcp_f32_e32 v6, v6
	v_sub_f32_e32 v4, 1.0, v4
	v_mul_f32_e32 v2, v2, v4
	v_and_b32_e32 v4, 0xffff0000, v5
	v_fmac_f32_e32 v3, v67, v4
	v_mul_f32_e32 v4, 0x3d372713, v3
	v_mul_f32_e32 v4, v3, v4
	v_fma_f32 v4, v3, v4, v3
	v_mul_f32_e32 v4, 0x3f4c422a, v4
	v_add_f32_e32 v4, v4, v4
	v_mul_f32_e32 v4, 0x3fb8aa3b, v4
	v_exp_f32_e32 v4, v4
	v_sub_f32_e32 v6, 1.0, v6
	v_mul_f32_e32 v0, v0, v6
	v_cvt_pk_bf16_f32 v0, v0, v1
	v_add_f32_e32 v4, 1.0, v4
	v_rcp_f32_e32 v4, v4
	s_nop 0
	v_sub_f32_e32 v4, 1.0, v4
	v_mul_f32_e32 v3, v3, v4
	v_cvt_pk_bf16_f32 v1, v2, v3
	ds_write_b64 v234, v[0:1] offset:33280
	ds_read_b128 v[0:3], v220 offset:4352
	ds_read_b128 v[4:7], v220 offset:4416
	ds_read_b128 v[8:11], v220 offset:4480
	ds_read_b128 v[16:19], v220 offset:4544
	s_waitcnt lgkmcnt(3)
	v_mfma_f32_16x16x32_bf16 v[0:3], v[80:83], v[0:3], 0
	s_waitcnt lgkmcnt(2)
	v_mfma_f32_16x16x32_bf16 v[0:3], v[76:79], v[4:7], v[0:3]
	s_waitcnt lgkmcnt(1)
	v_mfma_f32_16x16x32_bf16 v[0:3], v[72:75], v[8:11], v[0:3]
	s_waitcnt lgkmcnt(0)
	v_mfma_f32_16x16x32_bf16 v[0:3], v[68:71], v[16:19], v[0:3]
	v_mov_b64_e32 v[4:5], v[242:243]
	s_nop 1
	v_lshlrev_b32_e32 v6, 16, v4
	v_and_b32_e32 v4, 0xffff0000, v4
	s_nop 2
	v_fma_f32 v1, v65, v4, v1
	v_mul_f32_e32 v4, 0x3d372713, v1
	v_mul_f32_e32 v4, v1, v4
	v_fma_f32 v4, v1, v4, v1
	v_mul_f32_e32 v4, 0x3f4c422a, v4
	v_add_f32_e32 v4, v4, v4
	v_mul_f32_e32 v4, 0x3fb8aa3b, v4
	v_exp_f32_e32 v4, v4
	v_fma_f32 v0, v64, v6, v0
	v_mul_f32_e32 v6, 0x3d372713, v0
	v_mul_f32_e32 v6, v0, v6
	v_add_f32_e32 v4, 1.0, v4
	v_rcp_f32_e32 v4, v4
	v_fma_f32 v6, v0, v6, v0
	v_mul_f32_e32 v6, 0x3f4c422a, v6
	v_add_f32_e32 v6, v6, v6
	v_sub_f32_e32 v4, 1.0, v4
	v_mul_f32_e32 v1, v1, v4
	v_lshlrev_b32_e32 v4, 16, v5
	v_fma_f32 v2, v66, v4, v2
	v_mul_f32_e32 v4, 0x3d372713, v2
	v_mul_f32_e32 v4, v2, v4
	v_fma_f32 v4, v2, v4, v2
	v_mul_f32_e32 v4, 0x3f4c422a, v4
	v_add_f32_e32 v4, v4, v4
	v_mul_f32_e32 v4, 0x3fb8aa3b, v4
	v_exp_f32_e32 v4, v4
	v_mul_f32_e32 v6, 0x3fb8aa3b, v6
	v_exp_f32_e32 v6, v6
	v_add_f32_e32 v4, 1.0, v4
	v_rcp_f32_e32 v4, v4
	v_add_f32_e32 v6, 1.0, v6
	v_rcp_f32_e32 v6, v6
	v_sub_f32_e32 v4, 1.0, v4
	v_mul_f32_e32 v2, v2, v4
	v_and_b32_e32 v4, 0xffff0000, v5
	v_fmac_f32_e32 v3, v67, v4
	v_mul_f32_e32 v4, 0x3d372713, v3
	v_mul_f32_e32 v4, v3, v4
	v_fma_f32 v4, v3, v4, v3
	v_mul_f32_e32 v4, 0x3f4c422a, v4
	v_add_f32_e32 v4, v4, v4
	v_mul_f32_e32 v4, 0x3fb8aa3b, v4
	v_exp_f32_e32 v4, v4
	v_sub_f32_e32 v6, 1.0, v6
	v_mul_f32_e32 v0, v0, v6
	v_cvt_pk_bf16_f32 v0, v0, v1
	v_add_f32_e32 v4, 1.0, v4
	v_rcp_f32_e32 v4, v4
	s_nop 0
	v_sub_f32_e32 v4, 1.0, v4
	v_mul_f32_e32 v3, v3, v4
	v_cvt_pk_bf16_f32 v1, v2, v3
	v_add_u32_e32 v2, v132, v155
	ds_write_b64 v2, v[0:1]
	v_lshl_or_b32 v0, s38, 7, v129
	v_ashrrev_i32_e32 v1, 31, v0
	v_lshl_add_u64 v[0:1], v[0:1], 2, s[16:17]
	global_load_dwordx2 v[112:113], v[0:1], off
	global_load_dwordx2 v[116:117], v[0:1], off offset:256
	s_waitcnt vmcnt(1)
	v_pk_mul_f32 v[2:3], v[112:113], v[112:113]
	s_nop 0
	v_sub_f32_e32 v2, v2, v3
	v_add_f32_e32 v3, v112, v112
	v_mul_f32_e32 v3, v113, v3
	v_mul_f32_e32 v4, v2, v2
	v_add_f32_e32 v2, v2, v2
	v_mul_f32_e32 v2, v3, v2
	v_fma_f32 v4, -v3, v3, v4
	v_mul_f32_e32 v3, v2, v2
	v_fma_f32 v3, v4, v4, -v3
	v_add_f32_e32 v4, v4, v4
	v_mul_f32_e32 v2, v2, v4
	v_mul_f32_e32 v4, v2, v2
	s_waitcnt vmcnt(0)
	v_pk_mul_f32 v[0:1], v[116:117], v[116:117]
	v_fma_f32 v228, v3, v3, -v4
	v_add_f32_e32 v3, v3, v3
	v_sub_f32_e32 v0, v0, v1
	v_add_f32_e32 v1, v116, v116
	v_mul_f32_e32 v229, v2, v3
	v_mul_f32_e32 v1, v117, v1
	v_mul_f32_e32 v2, v0, v0
	v_add_f32_e32 v0, v0, v0
	v_mul_f32_e32 v0, v1, v0
	v_fma_f32 v2, -v1, v1, v2
	v_mul_f32_e32 v1, v0, v0
	v_fma_f32 v1, v2, v2, -v1
	v_add_f32_e32 v2, v2, v2
	v_mul_f32_e32 v0, v0, v2
	v_mul_f32_e32 v2, v0, v0
	v_fma_f32 v230, v1, v1, -v2
	v_add_f32_e32 v1, v1, v1
	v_mul_f32_e32 v231, v0, v1
	v_lshl_add_u64 v[0:1], v[134:135], 0, s[10:11]
	s_or_b32 s10, s14, 1
	s_mov_b32 s11, s15
	s_lshl_b64 s[10:11], s[10:11], 10
	global_load_dwordx4 v[84:87], v[0:1], off
	v_lshl_add_u64 v[0:1], v[134:135], 0, s[10:11]
	s_or_b32 s10, s14, 2
	s_mov_b32 s11, s15
	s_lshl_b64 s[10:11], s[10:11], 10
	s_or_b32 s14, s14, 3
	global_load_dwordx4 v[88:91], v[0:1], off
	v_lshl_add_u64 v[0:1], v[134:135], 0, s[10:11]
	s_lshl_b64 s[10:11], s[14:15], 10
	s_lshl_b32 s14, s38, 4
	global_load_dwordx4 v[96:99], v[0:1], off
	v_lshl_add_u64 v[0:1], v[134:135], 0, s[10:11]
	v_or_b32_e32 v132, s14, v128
	global_load_dwordx4 v[92:95], v[0:1], off
	v_lshlrev_b64 v[0:1], 8, v[132:133]
	v_lshl_add_u64 v[0:1], v[138:139], 0, v[0:1]
	global_load_dwordx4 v[80:83], v[0:1], off
	global_load_dwordx4 v[76:79], v[0:1], off offset:64
	global_load_dwordx4 v[72:75], v[0:1], off offset:128
	global_load_dwordx4 v[68:71], v[0:1], off offset:192
	v_lshl_add_u64 v[0:1], s[14:15], 2, v[140:141]
	s_lshl_b32 s38, s38, 5
	global_load_dwordx4 v[64:67], v[0:1], off
	v_lshl_add_u64 v[118:119], v[144:145], 0, s[38:39]
	v_or_b32_e32 v0, s14, v151
	v_lshl_add_u32 v132, v0, 1, s3
	v_lshl_add_u64 v[0:1], v[118:119], 0, v[100:101]
	global_load_dwordx4 v[0:3], v[0:1], off
	v_lshl_add_u64 v[114:115], v[146:147], 0, s[38:39]
	v_lshl_add_u64 v[244:245], v[118:119], 0, v[106:107]
	v_lshl_add_u64 v[248:249], v[114:115], 0, v[102:103]
	v_lshl_add_u64 v[250:251], v[114:115], 0, v[104:105]
	v_lshl_add_u64 v[252:253], v[114:115], 0, v[108:109]
	v_lshl_add_u64 v[242:243], v[114:115], 0, v[110:111]
	global_load_dwordx4 v[244:247], v[244:245], off
	global_load_dwordx2 v[248:249], v[248:249], off
	global_load_dwordx2 v[250:251], v[250:251], off
	global_load_dwordx2 v[252:253], v[252:253], off
	global_load_dwordx2 v[242:243], v[242:243], off
	s_waitcnt vmcnt(0)
	v_mfma_f32_32x32x16_bf16 v[32:47], v[0:3], v[96:99], 0
	s_nop 11
	v_fma_f32 v235, 0, v113, v32
	v_mfma_f32_32x32x16_bf16 v[48:63], v[0:3], v[84:87], 0
	v_fmac_f32_e32 v235, 0, v112
	v_mfma_f32_32x32x16_bf16 v[16:31], v[0:3], v[88:91], 0
	s_nop 9
	v_fmamk_f32 v234, v113, 0x80000000, v48
	v_fmac_f32_e32 v234, 0, v112
	v_fma_f32 v238, -v113, v235, v49
	v_fmac_f32_e32 v238, v112, v234
	v_fma_f32 v234, v113, v234, v33
	v_fmac_f32_e32 v234, v112, v235
	v_fma_f32 v235, -v113, v234, v50
	v_fmac_f32_e32 v235, v112, v238
	v_fma_f32 v238, v113, v238, v34
	v_fmac_f32_e32 v238, v112, v234
	v_fma_f32 v234, -v113, v238, v51
	v_fmac_f32_e32 v234, v112, v235
	v_fma_f32 v235, v113, v235, v35
	v_fmac_f32_e32 v235, v112, v238
	v_fma_f32 v238, -v113, v235, v52
	v_fmac_f32_e32 v238, v112, v234
	v_fma_f32 v234, v113, v234, v36
	v_fmac_f32_e32 v234, v112, v235
	v_fma_f32 v235, -v113, v234, v53
	v_fmac_f32_e32 v235, v112, v238
	v_fma_f32 v238, v113, v238, v37
	v_fmac_f32_e32 v238, v112, v234
	v_fma_f32 v234, -v113, v238, v54
	v_fmac_f32_e32 v234, v112, v235
	v_fma_f32 v235, v113, v235, v38
	v_fmac_f32_e32 v235, v112, v238
	v_fma_f32 v238, -v113, v235, v55
	v_fmac_f32_e32 v238, v112, v234
	v_fma_f32 v234, v113, v234, v39
	v_fmac_f32_e32 v234, v112, v235
	v_fma_f32 v235, -v113, v234, v56
	v_fmac_f32_e32 v235, v112, v238
	v_fma_f32 v238, v113, v238, v40
	v_fmac_f32_e32 v238, v112, v234
	v_fma_f32 v234, -v113, v238, v57
	v_fmac_f32_e32 v234, v112, v235
	v_fma_f32 v235, v113, v235, v41
	v_fmac_f32_e32 v235, v112, v238
	v_fma_f32 v238, -v113, v235, v58
	v_fmac_f32_e32 v238, v112, v234
	v_fma_f32 v234, v113, v234, v42
	v_fmac_f32_e32 v234, v112, v235
	v_fma_f32 v235, -v113, v234, v59
	v_fmac_f32_e32 v235, v112, v238
	v_fma_f32 v238, v113, v238, v43
	v_fmac_f32_e32 v238, v112, v234
	v_fma_f32 v234, -v113, v238, v60
	v_fmac_f32_e32 v234, v112, v235
	v_fma_f32 v235, v113, v235, v44
	v_fmac_f32_e32 v235, v112, v238
	v_fma_f32 v238, -v113, v235, v61
	v_fmac_f32_e32 v238, v112, v234
	v_fma_f32 v234, v113, v234, v45
	v_fmac_f32_e32 v234, v112, v235
	v_fma_f32 v235, -v113, v234, v62
	v_fmac_f32_e32 v235, v112, v238
	v_fma_f32 v238, v113, v238, v46
	v_fmac_f32_e32 v238, v112, v234
	v_fma_f32 v234, -v113, v238, v63
	v_fmac_f32_e32 v234, v112, v235
	v_fma_f32 v235, v113, v235, v47
	v_fmac_f32_e32 v235, v112, v238
	ds_bpermute_b32 v238, v149, v234
	ds_bpermute_b32 v239, v149, v235
	v_mfma_f32_32x32x16_bf16 v[0:15], v[0:3], v[92:95], 0
	s_waitcnt lgkmcnt(1)
	v_cndmask_b32_e64 v240, v238, v234, s[0:1]
	s_waitcnt lgkmcnt(0)
	v_cndmask_b32_e64 v241, v239, v235, s[0:1]
	v_cndmask_b32_e64 v238, v234, v238, s[0:1]
	v_cndmask_b32_e64 v234, v235, v239, s[0:1]
	v_fma_f32 v239, -v229, v233, v240
	v_fmac_f32_e32 v241, v229, v232
	v_fmac_f32_e32 v239, v228, v232
	v_fmac_f32_e32 v241, v228, v233
	v_cndmask_b32_e64 v232, v239, v232, s[0:1]
	v_cndmask_b32_e64 v233, v241, v233, s[0:1]
	v_fma_f32 v48, -v113, v233, v48
	v_fma_f32 v32, v113, v232, v32
	v_fmac_f32_e32 v48, v112, v232
	v_fmac_f32_e32 v32, v112, v233
	v_fma_f32 v49, -v113, v32, v49
	v_fma_f32 v33, v113, v48, v33
	v_cvt_pk_bf16_f32 v232, v48, v32
	ds_write_b32 v137, v232
	v_fmac_f32_e32 v49, v112, v48
	v_fmac_f32_e32 v33, v112, v32
	v_cvt_pk_bf16_f32 v32, v49, v33
	ds_write_b32 v137, v32 offset:272
	v_fma_f32 v32, -v113, v33, v50
	v_fma_f32 v34, v113, v49, v34
	v_fmac_f32_e32 v32, v112, v49
	v_fmac_f32_e32 v34, v112, v33
	v_cvt_pk_bf16_f32 v33, v32, v34
	ds_write_b32 v137, v33 offset:544
	v_fma_f32 v33, -v113, v34, v51
	v_fmac_f32_e32 v33, v112, v32
	v_fma_f32 v32, v113, v32, v35
	v_fmac_f32_e32 v32, v112, v34
	v_cvt_pk_bf16_f32 v34, v33, v32
	ds_write_b32 v137, v34 offset:816
	v_fma_f32 v34, -v113, v32, v52
	v_fmac_f32_e32 v34, v112, v33
	v_fma_f32 v33, v113, v33, v36
	v_fmac_f32_e32 v33, v112, v32
	v_cvt_pk_bf16_f32 v32, v34, v33
	ds_write_b32 v137, v32 offset:1088
	v_fma_f32 v32, -v113, v33, v53
	v_fmac_f32_e32 v32, v112, v34
	v_fma_f32 v34, v113, v34, v37
	v_fmac_f32_e32 v34, v112, v33
	v_cvt_pk_bf16_f32 v33, v32, v34
	ds_write_b32 v137, v33 offset:1360
	v_fma_f32 v33, -v113, v34, v54
	v_fmac_f32_e32 v33, v112, v32
	v_fma_f32 v32, v113, v32, v38
	v_fmac_f32_e32 v32, v112, v34
	v_cvt_pk_bf16_f32 v34, v33, v32
	ds_write_b32 v137, v34 offset:1632
	v_fma_f32 v34, -v113, v32, v55
	v_fmac_f32_e32 v34, v112, v33
	v_fma_f32 v33, v113, v33, v39
	v_fmac_f32_e32 v33, v112, v32
	v_cvt_pk_bf16_f32 v32, v34, v33
	ds_write_b32 v137, v32 offset:1904
	v_fma_f32 v32, -v113, v33, v56
	v_fmac_f32_e32 v32, v112, v34
	v_fma_f32 v34, v113, v34, v40
	v_fmac_f32_e32 v34, v112, v33
	v_cvt_pk_bf16_f32 v33, v32, v34
	ds_write_b32 v137, v33 offset:2176
	v_fma_f32 v33, -v113, v34, v57
	v_fmac_f32_e32 v33, v112, v32
	v_fma_f32 v32, v113, v32, v41
	v_fmac_f32_e32 v32, v112, v34
	v_cvt_pk_bf16_f32 v34, v33, v32
	ds_write_b32 v137, v34 offset:2448
	v_fma_f32 v34, -v113, v32, v58
	v_fmac_f32_e32 v34, v112, v33
	v_fma_f32 v33, v113, v33, v42
	v_fmac_f32_e32 v33, v112, v32
	v_cvt_pk_bf16_f32 v32, v34, v33
	ds_write_b32 v137, v32 offset:2720
	v_fma_f32 v32, -v113, v33, v59
	v_fmac_f32_e32 v32, v112, v34
	v_fma_f32 v34, v113, v34, v43
	v_fmac_f32_e32 v34, v112, v33
	v_cvt_pk_bf16_f32 v33, v32, v34
	ds_write_b32 v137, v33 offset:2992
	v_fma_f32 v33, -v113, v34, v60
	v_fmac_f32_e32 v33, v112, v32
	v_fma_f32 v32, v113, v32, v44
	v_fmac_f32_e32 v32, v112, v34
	v_cvt_pk_bf16_f32 v34, v33, v32
	ds_write_b32 v137, v34 offset:3264
	v_fma_f32 v34, -v113, v32, v61
	v_fmac_f32_e32 v34, v112, v33
	v_fma_f32 v33, v113, v33, v45
	v_fmac_f32_e32 v33, v112, v32
	v_cvt_pk_bf16_f32 v32, v34, v33
	ds_write_b32 v137, v32 offset:3536
	v_fma_f32 v32, -v113, v33, v62
	v_fmac_f32_e32 v32, v112, v34
	v_fma_f32 v34, v113, v34, v46
	v_fmac_f32_e32 v34, v112, v33
	v_cvt_pk_bf16_f32 v33, v32, v34
	ds_write_b32 v137, v33 offset:3808
	v_fma_f32 v33, -v113, v34, v63
	v_fmac_f32_e32 v33, v112, v32
	v_fmac_f32_e32 v47, v113, v32
	v_fmac_f32_e32 v47, v112, v34
	v_cvt_pk_bf16_f32 v32, v33, v47
	v_fma_f32 v33, 0, v117, v0
	ds_write_b32 v137, v32 offset:4080
	v_fmamk_f32 v32, v117, 0x80000000, v16
	v_fmac_f32_e32 v33, 0, v116
	v_fmac_f32_e32 v32, 0, v116
	v_fma_f32 v34, -v117, v33, v17
	v_fmac_f32_e32 v34, v116, v32
	v_fma_f32 v32, v117, v32, v1
	v_fmac_f32_e32 v32, v116, v33
	v_fma_f32 v33, -v117, v32, v18
	v_fmac_f32_e32 v33, v116, v34
	v_fma_f32 v34, v117, v34, v2
	v_fmac_f32_e32 v34, v116, v32
	v_fma_f32 v32, -v117, v34, v19
	v_fmac_f32_e32 v32, v116, v33
	v_fma_f32 v33, v117, v33, v3
	v_fmac_f32_e32 v33, v116, v34
	v_fma_f32 v34, -v117, v33, v20
	v_fmac_f32_e32 v34, v116, v32
	v_fma_f32 v32, v117, v32, v4
	v_fmac_f32_e32 v32, v116, v33
	v_fma_f32 v33, -v117, v32, v21
	v_fmac_f32_e32 v33, v116, v34
	v_fma_f32 v34, v117, v34, v5
	v_fmac_f32_e32 v34, v116, v32
	v_fma_f32 v32, -v117, v34, v22
	v_fmac_f32_e32 v32, v116, v33
	v_fma_f32 v33, v117, v33, v6
	v_fmac_f32_e32 v33, v116, v34
	v_fma_f32 v34, -v117, v33, v23
	v_fmac_f32_e32 v34, v116, v32
	v_fma_f32 v32, v117, v32, v7
	v_fmac_f32_e32 v32, v116, v33
	v_fma_f32 v33, -v117, v32, v24
	v_fmac_f32_e32 v33, v116, v34
	v_fma_f32 v34, v117, v34, v8
	v_fmac_f32_e32 v34, v116, v32
	v_fma_f32 v32, -v117, v34, v25
	v_fmac_f32_e32 v32, v116, v33
	v_fma_f32 v33, v117, v33, v9
	v_fmac_f32_e32 v33, v116, v34
	v_fma_f32 v34, -v117, v33, v26
	v_fmac_f32_e32 v34, v116, v32
	v_fma_f32 v32, v117, v32, v10
	v_fmac_f32_e32 v32, v116, v33
	v_fma_f32 v33, -v117, v32, v27
	v_fmac_f32_e32 v33, v116, v34
	v_fma_f32 v34, v117, v34, v11
	v_fmac_f32_e32 v34, v116, v32
	v_fma_f32 v32, -v117, v34, v28
	v_fmac_f32_e32 v32, v116, v33
	v_fma_f32 v33, v117, v33, v12
	v_fmac_f32_e32 v33, v116, v34
	v_fma_f32 v34, -v117, v33, v29
	v_fmac_f32_e32 v34, v116, v32
	v_fma_f32 v32, v117, v32, v13
	v_fmac_f32_e32 v32, v116, v33
	v_fma_f32 v33, -v117, v32, v30
	v_fmac_f32_e32 v33, v116, v34
	v_fma_f32 v34, v117, v34, v14
	v_fmac_f32_e32 v34, v116, v32
	v_fma_f32 v32, -v117, v34, v31
	v_fmac_f32_e32 v32, v116, v33
	v_fma_f32 v33, v117, v33, v15
	v_fmac_f32_e32 v33, v116, v34
	ds_bpermute_b32 v34, v149, v32
	ds_bpermute_b32 v35, v149, v33
	v_fmac_f32_e32 v234, v229, v239
	v_fma_f32 v235, -v229, v241, v238
	v_fmac_f32_e32 v234, v228, v241
	s_waitcnt lgkmcnt(1)
	v_cndmask_b32_e64 v36, v34, v32, s[0:1]
	s_waitcnt lgkmcnt(0)
	v_cndmask_b32_e64 v37, v35, v33, s[0:1]
	v_cndmask_b32_e64 v232, v33, v35, s[0:1]
	v_fma_f32 v33, -v231, v237, v36
	v_fmac_f32_e32 v37, v231, v236
	v_fmac_f32_e32 v33, v230, v236
	v_fmac_f32_e32 v37, v230, v237
	v_cndmask_b32_e64 v32, v32, v34, s[0:1]
	v_cndmask_b32_e64 v34, v33, v236, s[0:1]
	v_cndmask_b32_e64 v35, v37, v237, s[0:1]
	v_fma_f32 v16, -v117, v35, v16
	v_fma_f32 v0, v117, v34, v0
	v_fmac_f32_e32 v16, v116, v34
	v_fmac_f32_e32 v0, v116, v35
	v_fma_f32 v17, -v117, v0, v17
	v_fma_f32 v1, v117, v16, v1
	v_fma_f32 v233, -v231, v37, v32
	v_cvt_pk_bf16_f32 v32, v16, v0
	ds_write_b32 v137, v32 offset:128
	v_fmac_f32_e32 v17, v116, v16
	v_fmac_f32_e32 v1, v116, v0
	v_cvt_pk_bf16_f32 v0, v17, v1
	ds_write_b32 v137, v0 offset:400
	v_fma_f32 v0, -v117, v1, v18
	v_fma_f32 v2, v117, v17, v2
	v_fmac_f32_e32 v0, v116, v17
	v_fmac_f32_e32 v2, v116, v1
	v_cvt_pk_bf16_f32 v1, v0, v2
	ds_write_b32 v137, v1 offset:672
	v_fma_f32 v1, -v117, v2, v19
	v_fmac_f32_e32 v1, v116, v0
	v_fma_f32 v0, v117, v0, v3
	v_fmac_f32_e32 v0, v116, v2
	v_cvt_pk_bf16_f32 v2, v1, v0
	ds_write_b32 v137, v2 offset:944
	v_fma_f32 v2, -v117, v0, v20
	v_fmac_f32_e32 v2, v116, v1
	v_fma_f32 v1, v117, v1, v4
	v_fmac_f32_e32 v1, v116, v0
	v_cvt_pk_bf16_f32 v0, v2, v1
	ds_write_b32 v137, v0 offset:1216
	v_fma_f32 v0, -v117, v1, v21
	v_fmac_f32_e32 v0, v116, v2
	v_fma_f32 v2, v117, v2, v5
	v_fmac_f32_e32 v2, v116, v1
	v_cvt_pk_bf16_f32 v1, v0, v2
	ds_write_b32 v137, v1 offset:1488
	v_fma_f32 v1, -v117, v2, v22
	v_fmac_f32_e32 v1, v116, v0
	v_fma_f32 v0, v117, v0, v6
	v_fmac_f32_e32 v0, v116, v2
	v_cvt_pk_bf16_f32 v2, v1, v0
	ds_write_b32 v137, v2 offset:1760
	v_fma_f32 v2, -v117, v0, v23
	v_fmac_f32_e32 v2, v116, v1
	v_fma_f32 v1, v117, v1, v7
	v_fmac_f32_e32 v1, v116, v0
	v_cvt_pk_bf16_f32 v0, v2, v1
	ds_write_b32 v137, v0 offset:2032
	v_fma_f32 v0, -v117, v1, v24
	v_fmac_f32_e32 v0, v116, v2
	v_fma_f32 v2, v117, v2, v8
	v_fmac_f32_e32 v2, v116, v1
	v_cvt_pk_bf16_f32 v1, v0, v2
	ds_write_b32 v137, v1 offset:2304
	v_fma_f32 v1, -v117, v2, v25
	v_fmac_f32_e32 v1, v116, v0
	v_fma_f32 v0, v117, v0, v9
	v_fmac_f32_e32 v0, v116, v2
	v_cvt_pk_bf16_f32 v2, v1, v0
	ds_write_b32 v137, v2 offset:2576
	v_fma_f32 v2, -v117, v0, v26
	v_fmac_f32_e32 v2, v116, v1
	v_fma_f32 v1, v117, v1, v10
	v_fmac_f32_e32 v1, v116, v0
	v_cvt_pk_bf16_f32 v0, v2, v1
	ds_write_b32 v137, v0 offset:2848
	v_fma_f32 v0, -v117, v1, v27
	v_fmac_f32_e32 v0, v116, v2
	v_fma_f32 v2, v117, v2, v11
	v_fmac_f32_e32 v2, v116, v1
	v_cvt_pk_bf16_f32 v1, v0, v2
	ds_write_b32 v137, v1 offset:3120
	v_fma_f32 v1, -v117, v2, v28
	v_fmac_f32_e32 v1, v116, v0
	v_fma_f32 v0, v117, v0, v12
	v_fmac_f32_e32 v0, v116, v2
	v_cvt_pk_bf16_f32 v2, v1, v0
	ds_write_b32 v137, v2 offset:3392
	v_fma_f32 v2, -v117, v0, v29
	v_fmac_f32_e32 v2, v116, v1
	v_fma_f32 v1, v117, v1, v13
	v_fmac_f32_e32 v1, v116, v0
	v_cvt_pk_bf16_f32 v0, v2, v1
	ds_write_b32 v137, v0 offset:3664
	v_fma_f32 v0, -v117, v1, v30
	v_fmac_f32_e32 v0, v116, v2
	v_fma_f32 v2, v117, v2, v14
	v_fmac_f32_e32 v2, v116, v1
	v_cvt_pk_bf16_f32 v1, v0, v2
	ds_write_b32 v137, v1 offset:3936
	v_fma_f32 v1, -v117, v2, v31
	v_fmac_f32_e32 v15, v117, v0
	v_fmac_f32_e32 v1, v116, v0
	v_fmac_f32_e32 v15, v116, v2
	v_cvt_pk_bf16_f32 v0, v1, v15
	ds_write_b32 v137, v0 offset:4208
	ds_read_b128 v[0:3], v220
	ds_read_b128 v[4:7], v220 offset:64
	ds_read_b128 v[8:11], v220 offset:128
	ds_read_b128 v[16:19], v220 offset:192
	s_waitcnt lgkmcnt(3)
	v_mfma_f32_16x16x32_bf16 v[0:3], v[80:83], v[0:3], 0
	v_add_u32_e32 v236, v132, v153
	v_fmac_f32_e32 v232, v231, v33
	v_fmac_f32_e32 v233, v230, v33
	s_waitcnt lgkmcnt(2)
	v_mfma_f32_16x16x32_bf16 v[0:3], v[76:79], v[4:7], v[0:3]
	v_fmac_f32_e32 v232, v230, v37
	v_fmac_f32_e32 v235, v228, v239
	s_waitcnt lgkmcnt(1)
	v_mfma_f32_16x16x32_bf16 v[0:3], v[72:75], v[8:11], v[0:3]
	s_waitcnt lgkmcnt(0)
	v_mfma_f32_16x16x32_bf16 v[0:3], v[68:71], v[16:19], v[0:3]
	v_mov_b64_e32 v[4:5], v[248:249]
	s_nop 1
	v_lshlrev_b32_e32 v6, 16, v4
	v_and_b32_e32 v4, 0xffff0000, v4
	s_nop 2
	v_fma_f32 v1, v65, v4, v1
	v_mul_f32_e32 v4, 0x3d372713, v1
	v_mul_f32_e32 v4, v1, v4
	v_fma_f32 v4, v1, v4, v1
	v_mul_f32_e32 v4, 0x3f4c422a, v4
	v_add_f32_e32 v4, v4, v4
	v_mul_f32_e32 v4, 0x3fb8aa3b, v4
	v_exp_f32_e32 v4, v4
	v_fma_f32 v0, v64, v6, v0
	v_mul_f32_e32 v6, 0x3d372713, v0
	v_mul_f32_e32 v6, v0, v6
	v_add_f32_e32 v4, 1.0, v4
	v_rcp_f32_e32 v4, v4
	v_fma_f32 v6, v0, v6, v0
	v_mul_f32_e32 v6, 0x3f4c422a, v6
	v_add_f32_e32 v6, v6, v6
	v_sub_f32_e32 v4, 1.0, v4
	v_mul_f32_e32 v1, v1, v4
	v_lshlrev_b32_e32 v4, 16, v5
	v_fma_f32 v2, v66, v4, v2
	v_mul_f32_e32 v4, 0x3d372713, v2
	v_mul_f32_e32 v4, v2, v4
	v_fma_f32 v4, v2, v4, v2
	v_mul_f32_e32 v4, 0x3f4c422a, v4
	v_add_f32_e32 v4, v4, v4
	v_mul_f32_e32 v4, 0x3fb8aa3b, v4
	v_exp_f32_e32 v4, v4
	v_mul_f32_e32 v6, 0x3fb8aa3b, v6
	v_exp_f32_e32 v6, v6
	v_add_f32_e32 v4, 1.0, v4
	v_rcp_f32_e32 v4, v4
	v_add_f32_e32 v6, 1.0, v6
	v_rcp_f32_e32 v6, v6
	v_sub_f32_e32 v4, 1.0, v4
	v_mul_f32_e32 v2, v2, v4
	v_and_b32_e32 v4, 0xffff0000, v5
	v_fmac_f32_e32 v3, v67, v4
	v_mul_f32_e32 v4, 0x3d372713, v3
	v_mul_f32_e32 v4, v3, v4
	v_fma_f32 v4, v3, v4, v3
	v_mul_f32_e32 v4, 0x3f4c422a, v4
	v_add_f32_e32 v4, v4, v4
	v_mul_f32_e32 v4, 0x3fb8aa3b, v4
	v_exp_f32_e32 v4, v4
	v_sub_f32_e32 v6, 1.0, v6
	v_mul_f32_e32 v0, v0, v6
	v_cvt_pk_bf16_f32 v0, v0, v1
	v_add_f32_e32 v4, 1.0, v4
	v_rcp_f32_e32 v4, v4
	s_nop 0
	v_sub_f32_e32 v4, 1.0, v4
	v_mul_f32_e32 v3, v3, v4
	v_cvt_pk_bf16_f32 v1, v2, v3
	ds_write_b64 v236, v[0:1]
	ds_read_b128 v[0:3], v220 offset:4352
	ds_read_b128 v[4:7], v220 offset:4416
	ds_read_b128 v[8:11], v220 offset:4480
	ds_read_b128 v[16:19], v220 offset:4544
	s_waitcnt lgkmcnt(3)
	v_mfma_f32_16x16x32_bf16 v[0:3], v[80:83], v[0:3], 0
	s_waitcnt lgkmcnt(2)
	v_mfma_f32_16x16x32_bf16 v[0:3], v[76:79], v[4:7], v[0:3]
	s_waitcnt lgkmcnt(1)
	v_mfma_f32_16x16x32_bf16 v[0:3], v[72:75], v[8:11], v[0:3]
	s_waitcnt lgkmcnt(0)
	v_mfma_f32_16x16x32_bf16 v[0:3], v[68:71], v[16:19], v[0:3]
	v_mov_b64_e32 v[4:5], v[250:251]
	s_nop 1
	v_lshlrev_b32_e32 v6, 16, v4
	v_and_b32_e32 v4, 0xffff0000, v4
	s_nop 2
	v_fma_f32 v1, v65, v4, v1
	v_mul_f32_e32 v4, 0x3d372713, v1
	v_mul_f32_e32 v4, v1, v4
	v_fma_f32 v4, v1, v4, v1
	v_mul_f32_e32 v4, 0x3f4c422a, v4
	v_add_f32_e32 v4, v4, v4
	v_mul_f32_e32 v4, 0x3fb8aa3b, v4
	v_exp_f32_e32 v4, v4
	v_fma_f32 v0, v64, v6, v0
	v_mul_f32_e32 v6, 0x3d372713, v0
	v_mul_f32_e32 v6, v0, v6
	v_add_f32_e32 v4, 1.0, v4
	v_rcp_f32_e32 v4, v4
	v_fma_f32 v6, v0, v6, v0
	v_mul_f32_e32 v6, 0x3f4c422a, v6
	v_add_f32_e32 v6, v6, v6
	v_sub_f32_e32 v4, 1.0, v4
	v_mul_f32_e32 v1, v1, v4
	v_lshlrev_b32_e32 v4, 16, v5
	v_fma_f32 v2, v66, v4, v2
	v_mul_f32_e32 v4, 0x3d372713, v2
	v_mul_f32_e32 v4, v2, v4
	v_fma_f32 v4, v2, v4, v2
	v_mul_f32_e32 v4, 0x3f4c422a, v4
	v_add_f32_e32 v4, v4, v4
	v_mul_f32_e32 v4, 0x3fb8aa3b, v4
	v_exp_f32_e32 v4, v4
	v_mul_f32_e32 v6, 0x3fb8aa3b, v6
	v_exp_f32_e32 v6, v6
	v_add_f32_e32 v4, 1.0, v4
	v_rcp_f32_e32 v4, v4
	v_add_f32_e32 v6, 1.0, v6
	v_rcp_f32_e32 v6, v6
	v_sub_f32_e32 v4, 1.0, v4
	v_mul_f32_e32 v2, v2, v4
	v_and_b32_e32 v4, 0xffff0000, v5
	v_fmac_f32_e32 v3, v67, v4
	v_mul_f32_e32 v4, 0x3d372713, v3
	v_mul_f32_e32 v4, v3, v4
	v_fma_f32 v4, v3, v4, v3
	v_mul_f32_e32 v4, 0x3f4c422a, v4
	v_add_f32_e32 v4, v4, v4
	v_mul_f32_e32 v4, 0x3fb8aa3b, v4
	v_exp_f32_e32 v4, v4
	v_sub_f32_e32 v6, 1.0, v6
	v_mul_f32_e32 v0, v0, v6
	v_cvt_pk_bf16_f32 v0, v0, v1
	v_add_f32_e32 v4, 1.0, v4
	v_rcp_f32_e32 v4, v4
	s_nop 0
	v_sub_f32_e32 v4, 1.0, v4
	v_mul_f32_e32 v3, v3, v4
	v_cvt_pk_bf16_f32 v1, v2, v3
	ds_write_b64 v236, v[0:1] offset:16640
	v_mfma_f32_32x32x16_bf16 v[48:63], v[244:247], v[96:99], 0
	v_mfma_f32_32x32x16_bf16 v[32:47], v[244:247], v[84:87], 0
	s_nop 10
	v_fma_f32 v85, 0, v113, v48
	v_fmac_f32_e32 v85, 0, v112
	v_mfma_f32_32x32x16_bf16 v[16:31], v[244:247], v[88:91], 0
	v_fmamk_f32 v84, v113, 0x80000000, v32
	v_fmac_f32_e32 v84, 0, v112
	v_fma_f32 v86, -v113, v85, v33
	v_fmac_f32_e32 v86, v112, v84
	v_fma_f32 v84, v113, v84, v49
	v_fmac_f32_e32 v84, v112, v85
	v_fma_f32 v85, -v113, v84, v34
	v_fmac_f32_e32 v85, v112, v86
	v_fma_f32 v86, v113, v86, v50
	v_fmac_f32_e32 v86, v112, v84
	v_fma_f32 v84, -v113, v86, v35
	v_fmac_f32_e32 v84, v112, v85
	v_fma_f32 v85, v113, v85, v51
	v_fmac_f32_e32 v85, v112, v86
	v_fma_f32 v86, -v113, v85, v36
	v_fmac_f32_e32 v86, v112, v84
	v_fma_f32 v84, v113, v84, v52
	v_fmac_f32_e32 v84, v112, v85
	v_fma_f32 v85, -v113, v84, v37
	v_fmac_f32_e32 v85, v112, v86
	v_fma_f32 v86, v113, v86, v53
	v_fmac_f32_e32 v86, v112, v84
	v_fma_f32 v84, -v113, v86, v38
	v_fmac_f32_e32 v84, v112, v85
	v_fma_f32 v85, v113, v85, v54
	v_fmac_f32_e32 v85, v112, v86
	v_fma_f32 v86, -v113, v85, v39
	v_fmac_f32_e32 v86, v112, v84
	v_fma_f32 v84, v113, v84, v55
	v_fmac_f32_e32 v84, v112, v85
	v_fma_f32 v85, -v113, v84, v40
	v_fmac_f32_e32 v85, v112, v86
	v_fma_f32 v86, v113, v86, v56
	v_fmac_f32_e32 v86, v112, v84
	v_fma_f32 v84, -v113, v86, v41
	v_fmac_f32_e32 v84, v112, v85
	v_fma_f32 v85, v113, v85, v57
	v_fmac_f32_e32 v85, v112, v86
	v_fma_f32 v86, -v113, v85, v42
	v_fmac_f32_e32 v86, v112, v84
	v_fma_f32 v84, v113, v84, v58
	v_fmac_f32_e32 v84, v112, v85
	v_fma_f32 v85, -v113, v84, v43
	v_fmac_f32_e32 v85, v112, v86
	v_fma_f32 v86, v113, v86, v59
	v_fmac_f32_e32 v86, v112, v84
	v_fma_f32 v84, -v113, v86, v44
	v_fmac_f32_e32 v84, v112, v85
	v_fma_f32 v85, v113, v85, v60
	v_fmac_f32_e32 v85, v112, v86
	v_fma_f32 v86, -v113, v85, v45
	v_fmac_f32_e32 v86, v112, v84
	v_fma_f32 v84, v113, v84, v61
	v_fmac_f32_e32 v84, v112, v85
	v_fma_f32 v85, -v113, v84, v46
	v_fmac_f32_e32 v85, v112, v86
	v_fma_f32 v86, v113, v86, v62
	v_fmac_f32_e32 v86, v112, v84
	v_fma_f32 v84, -v113, v86, v47
	v_fmac_f32_e32 v84, v112, v85
	v_fma_f32 v85, v113, v85, v63
	v_fmac_f32_e32 v85, v112, v86
	ds_bpermute_b32 v86, v149, v84
	ds_bpermute_b32 v87, v149, v85
	v_mfma_f32_32x32x16_bf16 v[0:15], v[244:247], v[92:95], 0
	s_waitcnt lgkmcnt(1)
	v_cndmask_b32_e64 v84, v86, v84, s[0:1]
	s_waitcnt lgkmcnt(0)
	v_cndmask_b32_e64 v85, v87, v85, s[0:1]
	v_fma_f32 v84, -v229, v234, v84
	v_fmac_f32_e32 v84, v228, v235
	v_fmac_f32_e32 v85, v229, v235
	v_fmac_f32_e32 v85, v228, v234
	v_cndmask_b32_e64 v84, v84, v235, s[0:1]
	v_cndmask_b32_e64 v85, v85, v234, s[0:1]
	v_fma_f32 v48, v113, v84, v48
	v_fma_f32 v32, -v113, v85, v32
	v_fmac_f32_e32 v48, v112, v85
	v_fmac_f32_e32 v32, v112, v84
	v_fma_f32 v33, -v113, v48, v33
	v_cvt_pk_bf16_f32 v84, v32, v48
	v_fmac_f32_e32 v33, v112, v32
	v_fma_f32 v32, v113, v32, v49
	v_fmac_f32_e32 v32, v112, v48
	v_fma_f32 v34, -v113, v32, v34
	ds_write_b32 v137, v84
	v_cvt_pk_bf16_f32 v48, v33, v32
	v_fmac_f32_e32 v34, v112, v33
	v_fma_f32 v33, v113, v33, v50
	ds_write_b32 v137, v48 offset:272
	v_fmac_f32_e32 v33, v112, v32
	v_cvt_pk_bf16_f32 v32, v34, v33
	ds_write_b32 v137, v32 offset:544
	v_fma_f32 v32, -v113, v33, v35
	v_fmac_f32_e32 v32, v112, v34
	v_fma_f32 v34, v113, v34, v51
	v_fmac_f32_e32 v34, v112, v33
	v_cvt_pk_bf16_f32 v33, v32, v34
	ds_write_b32 v137, v33 offset:816
	v_fma_f32 v33, -v113, v34, v36
	v_fmac_f32_e32 v33, v112, v32
	v_fma_f32 v32, v113, v32, v52
	v_fmac_f32_e32 v32, v112, v34
	v_cvt_pk_bf16_f32 v34, v33, v32
	ds_write_b32 v137, v34 offset:1088
	v_fma_f32 v34, -v113, v32, v37
	v_fmac_f32_e32 v34, v112, v33
	v_fma_f32 v33, v113, v33, v53
	v_fmac_f32_e32 v33, v112, v32
	v_cvt_pk_bf16_f32 v32, v34, v33
	ds_write_b32 v137, v32 offset:1360
	v_fma_f32 v32, -v113, v33, v38
	v_fmac_f32_e32 v32, v112, v34
	v_fma_f32 v34, v113, v34, v54
	v_fmac_f32_e32 v34, v112, v33
	v_cvt_pk_bf16_f32 v33, v32, v34
	ds_write_b32 v137, v33 offset:1632
	v_fma_f32 v33, -v113, v34, v39
	v_fmac_f32_e32 v33, v112, v32
	v_fma_f32 v32, v113, v32, v55
	v_fmac_f32_e32 v32, v112, v34
	v_cvt_pk_bf16_f32 v34, v33, v32
	ds_write_b32 v137, v34 offset:1904
	v_fma_f32 v34, -v113, v32, v40
	v_fmac_f32_e32 v34, v112, v33
	v_fma_f32 v33, v113, v33, v56
	v_fmac_f32_e32 v33, v112, v32
	v_cvt_pk_bf16_f32 v32, v34, v33
	ds_write_b32 v137, v32 offset:2176
	v_fma_f32 v32, -v113, v33, v41
	v_fmac_f32_e32 v32, v112, v34
	v_fma_f32 v34, v113, v34, v57
	v_fmac_f32_e32 v34, v112, v33
	v_cvt_pk_bf16_f32 v33, v32, v34
	ds_write_b32 v137, v33 offset:2448
	v_fma_f32 v33, -v113, v34, v42
	v_fmac_f32_e32 v33, v112, v32
	v_fma_f32 v32, v113, v32, v58
	v_fmac_f32_e32 v32, v112, v34
	v_cvt_pk_bf16_f32 v34, v33, v32
	ds_write_b32 v137, v34 offset:2720
	v_fma_f32 v34, -v113, v32, v43
	v_fmac_f32_e32 v34, v112, v33
	v_fma_f32 v33, v113, v33, v59
	v_fmac_f32_e32 v33, v112, v32
	v_cvt_pk_bf16_f32 v32, v34, v33
	ds_write_b32 v137, v32 offset:2992
	v_fma_f32 v32, -v113, v33, v44
	v_fmac_f32_e32 v32, v112, v34
	v_fma_f32 v34, v113, v34, v60
	v_fmac_f32_e32 v34, v112, v33
	v_cvt_pk_bf16_f32 v33, v32, v34
	ds_write_b32 v137, v33 offset:3264
	v_fma_f32 v33, -v113, v34, v45
	v_fmac_f32_e32 v33, v112, v32
	v_fma_f32 v32, v113, v32, v61
	v_fmac_f32_e32 v32, v112, v34
	v_cvt_pk_bf16_f32 v34, v33, v32
	ds_write_b32 v137, v34 offset:3536
	v_fma_f32 v34, -v113, v32, v46
	v_fmac_f32_e32 v34, v112, v33
	v_fma_f32 v33, v113, v33, v62
	v_fmac_f32_e32 v33, v112, v32
	v_cvt_pk_bf16_f32 v32, v34, v33
	ds_write_b32 v137, v32 offset:3808
	v_fma_f32 v32, -v113, v33, v47
	v_fmac_f32_e32 v32, v112, v34
	v_fmac_f32_e32 v63, v113, v34
	v_fmac_f32_e32 v63, v112, v33
	v_cvt_pk_bf16_f32 v32, v32, v63
	v_fma_f32 v33, 0, v117, v0
	ds_write_b32 v137, v32 offset:4080
	v_fmamk_f32 v32, v117, 0x80000000, v16
	v_fmac_f32_e32 v33, 0, v116
	v_fmac_f32_e32 v32, 0, v116
	v_fma_f32 v34, -v117, v33, v17
	v_fmac_f32_e32 v34, v116, v32
	v_fma_f32 v32, v117, v32, v1
	v_fmac_f32_e32 v32, v116, v33
	v_fma_f32 v33, -v117, v32, v18
	v_fmac_f32_e32 v33, v116, v34
	v_fma_f32 v34, v117, v34, v2
	v_fmac_f32_e32 v34, v116, v32
	v_fma_f32 v32, -v117, v34, v19
	v_fmac_f32_e32 v32, v116, v33
	v_fma_f32 v33, v117, v33, v3
	v_fmac_f32_e32 v33, v116, v34
	v_fma_f32 v34, -v117, v33, v20
	v_fmac_f32_e32 v34, v116, v32
	v_fma_f32 v32, v117, v32, v4
	v_fmac_f32_e32 v32, v116, v33
	v_fma_f32 v33, -v117, v32, v21
	v_fmac_f32_e32 v33, v116, v34
	v_fma_f32 v34, v117, v34, v5
	v_fmac_f32_e32 v34, v116, v32
	v_fma_f32 v32, -v117, v34, v22
	v_fmac_f32_e32 v32, v116, v33
	v_fma_f32 v33, v117, v33, v6
	v_fmac_f32_e32 v33, v116, v34
	v_fma_f32 v34, -v117, v33, v23
	v_fmac_f32_e32 v34, v116, v32
	v_fma_f32 v32, v117, v32, v7
	v_fmac_f32_e32 v32, v116, v33
	v_fma_f32 v33, -v117, v32, v24
	v_fmac_f32_e32 v33, v116, v34
	v_fma_f32 v34, v117, v34, v8
	v_fmac_f32_e32 v34, v116, v32
	v_fma_f32 v32, -v117, v34, v25
	v_fmac_f32_e32 v32, v116, v33
	v_fma_f32 v33, v117, v33, v9
	v_fmac_f32_e32 v33, v116, v34
	v_fma_f32 v34, -v117, v33, v26
	v_fmac_f32_e32 v34, v116, v32
	v_fma_f32 v32, v117, v32, v10
	v_fmac_f32_e32 v32, v116, v33
	v_fma_f32 v33, -v117, v32, v27
	v_fmac_f32_e32 v33, v116, v34
	v_fma_f32 v34, v117, v34, v11
	v_fmac_f32_e32 v34, v116, v32
	v_fma_f32 v32, -v117, v34, v28
	v_fmac_f32_e32 v32, v116, v33
	v_fma_f32 v33, v117, v33, v12
	v_fmac_f32_e32 v33, v116, v34
	v_fma_f32 v34, -v117, v33, v29
	v_fmac_f32_e32 v34, v116, v32
	v_fma_f32 v32, v117, v32, v13
	v_fmac_f32_e32 v32, v116, v33
	v_fma_f32 v33, -v117, v32, v30
	v_fmac_f32_e32 v33, v116, v34
	v_fma_f32 v34, v117, v34, v14
	v_fmac_f32_e32 v34, v116, v32
	v_fma_f32 v32, -v117, v34, v31
	v_fmac_f32_e32 v32, v116, v33
	v_fma_f32 v33, v117, v33, v15
	v_fmac_f32_e32 v33, v116, v34
	ds_bpermute_b32 v34, v149, v32
	ds_bpermute_b32 v35, v149, v33
	s_waitcnt lgkmcnt(1)
	v_cndmask_b32_e64 v32, v34, v32, s[0:1]
	s_waitcnt lgkmcnt(0)
	v_cndmask_b32_e64 v33, v35, v33, s[0:1]
	v_fma_f32 v32, -v231, v232, v32
	v_fmac_f32_e32 v33, v231, v233
	v_fmac_f32_e32 v32, v230, v233
	v_fmac_f32_e32 v33, v230, v232
	v_cndmask_b32_e64 v32, v32, v233, s[0:1]
	v_cndmask_b32_e64 v33, v33, v232, s[0:1]
	v_fma_f32 v16, -v117, v33, v16
	v_fma_f32 v0, v117, v32, v0
	v_fmac_f32_e32 v16, v116, v32
	v_fmac_f32_e32 v0, v116, v33
	v_fma_f32 v17, -v117, v0, v17
	v_fma_f32 v1, v117, v16, v1
	v_cvt_pk_bf16_f32 v32, v16, v0
	ds_write_b32 v137, v32 offset:128
	v_fmac_f32_e32 v17, v116, v16
	v_fmac_f32_e32 v1, v116, v0
	v_cvt_pk_bf16_f32 v0, v17, v1
	ds_write_b32 v137, v0 offset:400
	v_fma_f32 v0, -v117, v1, v18
	v_fma_f32 v2, v117, v17, v2
	v_fmac_f32_e32 v0, v116, v17
	v_fmac_f32_e32 v2, v116, v1
	v_cvt_pk_bf16_f32 v1, v0, v2
	ds_write_b32 v137, v1 offset:672
	v_fma_f32 v1, -v117, v2, v19
	v_fmac_f32_e32 v1, v116, v0
	v_fma_f32 v0, v117, v0, v3
	v_fmac_f32_e32 v0, v116, v2
	v_cvt_pk_bf16_f32 v2, v1, v0
	ds_write_b32 v137, v2 offset:944
	v_fma_f32 v2, -v117, v0, v20
	v_fmac_f32_e32 v2, v116, v1
	v_fma_f32 v1, v117, v1, v4
	v_fmac_f32_e32 v1, v116, v0
	v_cvt_pk_bf16_f32 v0, v2, v1
	ds_write_b32 v137, v0 offset:1216
	v_fma_f32 v0, -v117, v1, v21
	v_fmac_f32_e32 v0, v116, v2
	v_fma_f32 v2, v117, v2, v5
	v_fmac_f32_e32 v2, v116, v1
	v_cvt_pk_bf16_f32 v1, v0, v2
	ds_write_b32 v137, v1 offset:1488
	v_fma_f32 v1, -v117, v2, v22
	v_fmac_f32_e32 v1, v116, v0
	v_fma_f32 v0, v117, v0, v6
	v_fmac_f32_e32 v0, v116, v2
	v_cvt_pk_bf16_f32 v2, v1, v0
	ds_write_b32 v137, v2 offset:1760
	v_fma_f32 v2, -v117, v0, v23
	v_fmac_f32_e32 v2, v116, v1
	v_fma_f32 v1, v117, v1, v7
	v_fmac_f32_e32 v1, v116, v0
	v_cvt_pk_bf16_f32 v0, v2, v1
	ds_write_b32 v137, v0 offset:2032
	v_fma_f32 v0, -v117, v1, v24
	v_fmac_f32_e32 v0, v116, v2
	v_fma_f32 v2, v117, v2, v8
	v_fmac_f32_e32 v2, v116, v1
	v_cvt_pk_bf16_f32 v1, v0, v2
	ds_write_b32 v137, v1 offset:2304
	v_fma_f32 v1, -v117, v2, v25
	v_fmac_f32_e32 v1, v116, v0
	v_fma_f32 v0, v117, v0, v9
	v_fmac_f32_e32 v0, v116, v2
	v_cvt_pk_bf16_f32 v2, v1, v0
	ds_write_b32 v137, v2 offset:2576
	v_fma_f32 v2, -v117, v0, v26
	v_fmac_f32_e32 v2, v116, v1
	v_fma_f32 v1, v117, v1, v10
	v_fmac_f32_e32 v1, v116, v0
	v_cvt_pk_bf16_f32 v0, v2, v1
	ds_write_b32 v137, v0 offset:2848
	v_fma_f32 v0, -v117, v1, v27
	v_fmac_f32_e32 v0, v116, v2
	v_fma_f32 v2, v117, v2, v11
	v_fmac_f32_e32 v2, v116, v1
	v_cvt_pk_bf16_f32 v1, v0, v2
	ds_write_b32 v137, v1 offset:3120
	v_fma_f32 v1, -v117, v2, v28
	v_fmac_f32_e32 v1, v116, v0
	v_fma_f32 v0, v117, v0, v12
	v_fmac_f32_e32 v0, v116, v2
	v_cvt_pk_bf16_f32 v2, v1, v0
	ds_write_b32 v137, v2 offset:3392
	v_fma_f32 v2, -v117, v0, v29
	v_fmac_f32_e32 v2, v116, v1
	v_fma_f32 v1, v117, v1, v13
	v_fmac_f32_e32 v1, v116, v0
	v_cvt_pk_bf16_f32 v0, v2, v1
	ds_write_b32 v137, v0 offset:3664
	v_fma_f32 v0, -v117, v1, v30
	v_fmac_f32_e32 v0, v116, v2
	v_fma_f32 v2, v117, v2, v14
	v_fmac_f32_e32 v2, v116, v1
	v_cvt_pk_bf16_f32 v1, v0, v2
	ds_write_b32 v137, v1 offset:3936
	v_fma_f32 v1, -v117, v2, v31
	v_fmac_f32_e32 v15, v117, v0
	v_fmac_f32_e32 v1, v116, v0
	v_fmac_f32_e32 v15, v116, v2
	v_cvt_pk_bf16_f32 v0, v1, v15
	ds_write_b32 v137, v0 offset:4208
	ds_read_b128 v[0:3], v220
	ds_read_b128 v[4:7], v220 offset:64
	ds_read_b128 v[8:11], v220 offset:128
	ds_read_b128 v[16:19], v220 offset:192
	s_waitcnt lgkmcnt(3)
	v_mfma_f32_16x16x32_bf16 v[0:3], v[80:83], v[0:3], 0
	s_waitcnt lgkmcnt(2)
	v_mfma_f32_16x16x32_bf16 v[0:3], v[76:79], v[4:7], v[0:3]
	s_waitcnt lgkmcnt(1)
	v_mfma_f32_16x16x32_bf16 v[0:3], v[72:75], v[8:11], v[0:3]
	s_waitcnt lgkmcnt(0)
	v_mfma_f32_16x16x32_bf16 v[0:3], v[68:71], v[16:19], v[0:3]
	v_mov_b64_e32 v[4:5], v[252:253]
	s_nop 1
	v_lshlrev_b32_e32 v6, 16, v4
	v_and_b32_e32 v4, 0xffff0000, v4
	s_nop 2
	v_fma_f32 v1, v65, v4, v1
	v_mul_f32_e32 v4, 0x3d372713, v1
	v_mul_f32_e32 v4, v1, v4
	v_fma_f32 v4, v1, v4, v1
	v_mul_f32_e32 v4, 0x3f4c422a, v4
	v_add_f32_e32 v4, v4, v4
	v_mul_f32_e32 v4, 0x3fb8aa3b, v4
	v_exp_f32_e32 v4, v4
	v_fma_f32 v0, v64, v6, v0
	v_mul_f32_e32 v6, 0x3d372713, v0
	v_mul_f32_e32 v6, v0, v6
	v_add_f32_e32 v4, 1.0, v4
	v_rcp_f32_e32 v4, v4
	v_fma_f32 v6, v0, v6, v0
	v_mul_f32_e32 v6, 0x3f4c422a, v6
	v_add_f32_e32 v6, v6, v6
	v_sub_f32_e32 v4, 1.0, v4
	v_mul_f32_e32 v1, v1, v4
	v_lshlrev_b32_e32 v4, 16, v5
	v_fma_f32 v2, v66, v4, v2
	v_mul_f32_e32 v4, 0x3d372713, v2
	v_mul_f32_e32 v4, v2, v4
	v_fma_f32 v4, v2, v4, v2
	v_mul_f32_e32 v4, 0x3f4c422a, v4
	v_add_f32_e32 v4, v4, v4
	v_mul_f32_e32 v4, 0x3fb8aa3b, v4
	v_exp_f32_e32 v4, v4
	v_mul_f32_e32 v6, 0x3fb8aa3b, v6
	v_exp_f32_e32 v6, v6
	v_add_f32_e32 v4, 1.0, v4
	v_rcp_f32_e32 v4, v4
	v_add_f32_e32 v6, 1.0, v6
	v_rcp_f32_e32 v6, v6
	v_sub_f32_e32 v4, 1.0, v4
	v_mul_f32_e32 v2, v2, v4
	v_and_b32_e32 v4, 0xffff0000, v5
	v_fmac_f32_e32 v3, v67, v4
	v_mul_f32_e32 v4, 0x3d372713, v3
	v_mul_f32_e32 v4, v3, v4
	v_fma_f32 v4, v3, v4, v3
	v_mul_f32_e32 v4, 0x3f4c422a, v4
	v_add_f32_e32 v4, v4, v4
	v_mul_f32_e32 v4, 0x3fb8aa3b, v4
	v_exp_f32_e32 v4, v4
	v_sub_f32_e32 v6, 1.0, v6
	v_mul_f32_e32 v0, v0, v6
	v_cvt_pk_bf16_f32 v0, v0, v1
	v_add_f32_e32 v4, 1.0, v4
	v_rcp_f32_e32 v4, v4
	s_nop 0
	v_sub_f32_e32 v4, 1.0, v4
	v_mul_f32_e32 v3, v3, v4
	v_cvt_pk_bf16_f32 v1, v2, v3
	ds_write_b64 v236, v[0:1] offset:33280
	ds_read_b128 v[0:3], v220 offset:4352
	ds_read_b128 v[4:7], v220 offset:4416
	ds_read_b128 v[8:11], v220 offset:4480
	ds_read_b128 v[16:19], v220 offset:4544
	s_waitcnt lgkmcnt(3)
	v_mfma_f32_16x16x32_bf16 v[0:3], v[80:83], v[0:3], 0
	s_waitcnt lgkmcnt(2)
	v_mfma_f32_16x16x32_bf16 v[0:3], v[76:79], v[4:7], v[0:3]
	s_waitcnt lgkmcnt(1)
	v_mfma_f32_16x16x32_bf16 v[0:3], v[72:75], v[8:11], v[0:3]
	s_waitcnt lgkmcnt(0)
	v_mfma_f32_16x16x32_bf16 v[0:3], v[68:71], v[16:19], v[0:3]
	v_mov_b64_e32 v[4:5], v[242:243]
	s_nop 1
	v_lshlrev_b32_e32 v6, 16, v4
	v_and_b32_e32 v4, 0xffff0000, v4
	s_nop 2
	v_fma_f32 v1, v65, v4, v1
	v_mul_f32_e32 v4, 0x3d372713, v1
	v_mul_f32_e32 v4, v1, v4
	v_fma_f32 v4, v1, v4, v1
	v_mul_f32_e32 v4, 0x3f4c422a, v4
	v_add_f32_e32 v4, v4, v4
	v_mul_f32_e32 v4, 0x3fb8aa3b, v4
	v_exp_f32_e32 v4, v4
	v_fma_f32 v0, v64, v6, v0
	v_mul_f32_e32 v6, 0x3d372713, v0
	v_mul_f32_e32 v6, v0, v6
	v_add_f32_e32 v4, 1.0, v4
	v_rcp_f32_e32 v4, v4
	v_fma_f32 v6, v0, v6, v0
	v_mul_f32_e32 v6, 0x3f4c422a, v6
	v_add_f32_e32 v6, v6, v6
	v_sub_f32_e32 v4, 1.0, v4
	v_mul_f32_e32 v1, v1, v4
	v_lshlrev_b32_e32 v4, 16, v5
	v_fma_f32 v2, v66, v4, v2
	v_mul_f32_e32 v4, 0x3d372713, v2
	v_mul_f32_e32 v4, v2, v4
	v_fma_f32 v4, v2, v4, v2
	v_mul_f32_e32 v4, 0x3f4c422a, v4
	v_add_f32_e32 v4, v4, v4
	v_mul_f32_e32 v4, 0x3fb8aa3b, v4
	v_exp_f32_e32 v4, v4
	v_mul_f32_e32 v6, 0x3fb8aa3b, v6
	v_exp_f32_e32 v6, v6
	v_add_f32_e32 v4, 1.0, v4
	v_rcp_f32_e32 v4, v4
	v_add_f32_e32 v6, 1.0, v6
	v_rcp_f32_e32 v6, v6
	v_sub_f32_e32 v4, 1.0, v4
	v_mul_f32_e32 v2, v2, v4
	v_and_b32_e32 v4, 0xffff0000, v5
	v_fmac_f32_e32 v3, v67, v4
	v_mul_f32_e32 v4, 0x3d372713, v3
	v_mul_f32_e32 v4, v3, v4
	v_fma_f32 v4, v3, v4, v3
	v_mul_f32_e32 v4, 0x3f4c422a, v4
	v_add_f32_e32 v4, v4, v4
	v_mul_f32_e32 v4, 0x3fb8aa3b, v4
	v_exp_f32_e32 v4, v4
	v_sub_f32_e32 v6, 1.0, v6
	v_mul_f32_e32 v0, v0, v6
	v_cvt_pk_bf16_f32 v0, v0, v1
	v_add_f32_e32 v4, 1.0, v4
	v_rcp_f32_e32 v4, v4
	s_nop 0
	v_sub_f32_e32 v4, 1.0, v4
	v_mul_f32_e32 v3, v3, v4
	v_cvt_pk_bf16_f32 v1, v2, v3
	v_add_u32_e32 v2, v132, v155
	ds_write_b64 v2, v[0:1]
	s_cbranch_vccnz .LBB0_405
	s_waitcnt lgkmcnt(0)
	s_barrier
	global_load_dwordx4 v[68:71], v[156:157], off
	global_load_dwordx4 v[40:43], v[156:157], off offset:1024
	global_load_dwordx4 v[76:79], v[156:157], off offset:2048
	global_load_dwordx4 v[88:91], v[156:157], off offset:3072
	global_load_dwordx4 v[32:35], v[158:159], off
	global_load_dwordx4 v[36:39], v[160:161], off
	global_load_dwordx4 v[44:47], v[162:163], off
	global_load_dwordx4 v[80:83], v[164:165], off
	global_load_dwordx4 v[72:75], v[166:167], off
	global_load_dwordx4 v[84:87], v[168:169], off
	global_load_dwordx4 v[92:95], v[170:171], off
	global_load_dwordx4 v[96:99], v[172:173], off
	v_mov_b32_e32 v0, 0
	s_mov_b32 s6, -4
	v_mov_b32_e32 v132, v219
	v_mov_b32_e32 v224, v218
	v_mov_b64_e32 v[194:195], v[174:175]
	v_mov_b32_e32 v1, v0
	v_mov_b32_e32 v2, v0
	v_mov_b32_e32 v3, v0
	v_mov_b32_e32 v8, v0
	v_mov_b32_e32 v9, v0
	v_mov_b32_e32 v10, v0
	v_mov_b32_e32 v11, v0
	v_mov_b32_e32 v4, v0
	v_mov_b32_e32 v5, v0
	v_mov_b32_e32 v6, v0
	v_mov_b32_e32 v7, v0
	v_mov_b32_e32 v12, v0
	v_mov_b32_e32 v13, v0
	v_mov_b32_e32 v14, v0
	v_mov_b32_e32 v15, v0
	v_mov_b32_e32 v16, v0
	v_mov_b32_e32 v17, v0
	v_mov_b32_e32 v18, v0
	v_mov_b32_e32 v19, v0
	v_mov_b32_e32 v20, v0
	v_mov_b32_e32 v21, v0
	v_mov_b32_e32 v22, v0
	v_mov_b32_e32 v23, v0
	v_mov_b32_e32 v24, v0
	v_mov_b32_e32 v25, v0
	v_mov_b32_e32 v26, v0
	v_mov_b32_e32 v27, v0
	v_mov_b32_e32 v28, v0
	v_mov_b32_e32 v29, v0
	v_mov_b32_e32 v30, v0
	v_mov_b32_e32 v31, v0
	v_mov_b32_e32 v48, v0
	v_mov_b32_e32 v49, v0
	v_mov_b32_e32 v50, v0
	v_mov_b32_e32 v51, v0
	v_mov_b32_e32 v52, v0
	v_mov_b32_e32 v53, v0
	v_mov_b32_e32 v54, v0
	v_mov_b32_e32 v55, v0
	v_mov_b32_e32 v56, v0
	v_mov_b32_e32 v57, v0
	v_mov_b32_e32 v58, v0
	v_mov_b32_e32 v59, v0
	v_mov_b32_e32 v60, v0
	v_mov_b32_e32 v61, v0
	v_mov_b32_e32 v62, v0
	v_mov_b32_e32 v63, v0
	v_mov_b32_e32 v64, v0
	v_mov_b32_e32 v65, v0
	v_mov_b32_e32 v66, v0
	v_mov_b32_e32 v67, v0
	v_mov_b32_e32 v100, v0
	v_mov_b32_e32 v101, v0
	v_mov_b32_e32 v102, v0
	v_mov_b32_e32 v103, v0
	v_mov_b32_e32 v104, v0
	v_mov_b32_e32 v105, v0
	v_mov_b32_e32 v106, v0
	v_mov_b32_e32 v107, v0
	v_mov_b32_e32 v108, v0
	v_mov_b32_e32 v109, v0
	v_mov_b32_e32 v110, v0
	v_mov_b32_e32 v111, v0
	s_branch .LBB0_408
